# attention rewritten: LDS-DMA K/V rings (4 slots), K fragments read one tile ahead beside PV MFMAs, V reads spread 2 per QK MFMA, exp/sum interleaved with QK(t+1), mask/max with PV(t); dead probe cases
# speedup vs baseline: 1.0220x; 1.0096x over previous
.LBB0_28:
	s_and_b32 s30, s0, 0xff
	s_waitcnt lgkmcnt(0)
	v_writelane_b32 v252, s2, 31
	s_add_u32 s0, s50, 0x3400000
	s_addc_u32 s1, s51, 0
	v_writelane_b32 v252, s3, 32
	v_writelane_b32 v252, s0, 33
	s_mov_b32 s28, 0x100000
	s_mov_b32 s84, s58
	v_writelane_b32 v252, s1, 34
	s_add_u32 s0, s50, 0x5500000
	s_addc_u32 s1, s51, 0
	v_writelane_b32 v252, s0, 35
	s_nop 1
	v_writelane_b32 v252, s1, 36
	s_add_u32 s0, s50, 0x10800000
	s_addc_u32 s1, s51, 0
	v_writelane_b32 v252, s0, 37
	s_cmp_lt_i32 s30, 9
	s_nop 0
	v_writelane_b32 v252, s1, 38
	s_mov_b64 s[0:1], -1
	s_cbranch_scc1 .LBB0_715
	s_and_b32 s31, 0xffff, s30
	s_cmp_lt_i32 s31, 13
	s_cbranch_scc1 .LBB0_585
	s_add_u32 s20, s50, 0xe100000
	s_addc_u32 s21, s51, 0
	s_cmp_lt_i32 s31, 15
	s_cbranch_scc1 .LBB0_515
	s_cmp_lt_i32 s31, 17
	s_cbranch_scc1 .LBB0_460
	s_cmp_lt_i32 s31, 19
	s_cbranch_scc1 .LBB0_76
	s_cmp_eq_u32 s31, 19
	s_cbranch_scc0 .LBB0_75
.LBB0_75:
	s_mov_b64 s[0:1], 0
.LBB0_76:
	s_andn2_b64 vcc, exec, s[0:1]
	s_cbranch_vccnz .LBB0_459
	s_cmp_eq_u32 s31, 17
	s_cbranch_scc0 .LBB0_459
.LBB0_459:
	s_mov_b64 s[0:1], 0

.LBB0_715:
	s_andn2_b64 vcc, exec, s[0:1]
	s_cbranch_vccnz .LBB0_1495
	s_and_b32 s23, 0xffff, s30
	v_readlane_b32 s80, v252, 35
	s_cmp_lt_i32 s23, 4
	s_mov_b64 s[0:1], -1
	s_movk_i32 s20, 0x1000
	s_movk_i32 s30, 0x3bf
	s_mov_b32 s31, 0x10000
	s_mov_b64 s[24:25], 0x165800
	v_readlane_b32 s81, v252, 36
	v_writelane_b32 v252, s23, 39
	s_cbranch_scc1 .LBB0_1294
	v_readlane_b32 s28, v252, 37
	s_cmp_lt_i32 s23, 6
	v_readlane_b32 s29, v252, 38
	s_cbranch_scc1 .LBB0_837
	s_cmp_lt_i32 s23, 7
	s_cbranch_scc1 .LBB0_830
	s_cmp_gt_i32 s23, 7
	s_cbranch_scc0 .LBB0_764
.LBB0_763:
	s_mov_b64 s[0:1], 0

.LBB0_786:
	v_lshrrev_b32_e32 v235, 6, v186
	v_and_b32_e32 v236, 63, v186
	v_readfirstlane_b32 s3, v235
	v_and_b32_e32 v237, 31, v236
	v_lshrrev_b32_e32 v238, 5, v236
	v_lshlrev_b32_e32 v229, 2, v238
	v_lshrrev_b32_e32 v239, 3, v186
	v_and_b32_e32 v240, 7, v186
	v_mul_u32_u24_e32 v33, 0x2cb0, v239
	v_bfe_u32 v241, v239, 1, 3
	v_xor_b32_e32 v241, v240, v241
	v_lshl_add_u32 v221, v241, 4, v33
	v_add_u32_e32 v221, 0x400, v221
	v_bfe_u32 v241, v239, 1, 1
	v_lshlrev_b32_e32 v241, 2, v241
	v_xor_b32_e32 v241, v240, v241
	v_lshl_add_u32 v222, v241, 4, v33
	v_add_u32_e32 v222, 0x800, v222
	v_bfe_u32 v241, v237, 1, 3
	v_or_b32_e32 v242, 0, v238
	v_xor_b32_e32 v242, v242, v241
	v_lshlrev_b32_e32 v242, 4, v242
	v_lshl_add_u32 v223, v237, 7, v242
	v_or_b32_e32 v242, 2, v238
	v_xor_b32_e32 v242, v242, v241
	v_lshlrev_b32_e32 v242, 4, v242
	v_lshl_add_u32 v224, v237, 7, v242
	v_or_b32_e32 v242, 4, v238
	v_xor_b32_e32 v242, v242, v241
	v_lshlrev_b32_e32 v242, 4, v242
	v_lshl_add_u32 v225, v237, 7, v242
	v_or_b32_e32 v242, 6, v238
	v_xor_b32_e32 v242, v242, v241
	v_lshlrev_b32_e32 v242, 4, v242
	v_lshl_add_u32 v226, v237, 7, v242
	v_and_b32_e32 v239, 3, v236
	v_bfe_u32 v240, v236, 2, 2
	v_bfe_u32 v241, v236, 4, 1
	v_lshrrev_b32_e32 v242, 1, v239
	v_lshl_add_u32 v241, v241, 1, v242
	v_lshrrev_b32_e32 v242, 1, v240
	v_lshl_add_u32 v33, v242, 2, v241
	v_xor_b32_e32 v242, 1, v242
	v_lshl_add_u32 v197, v242, 2, v241
	v_lshl_add_u32 v240, v238, 2, v240
	v_and_b32_e32 v239, 1, v239
	v_lshlrev_b32_e32 v239, 3, v239
	v_lshl_add_u32 v240, v240, 7, v239
	v_lshl_add_u32 v227, v33, 4, v240
	v_lshl_add_u32 v228, v197, 4, v240
	v_add_u32_e32 v227, 0x8000, v227
	v_add_u32_e32 v228, 0x8000, v228
	s_lshl_b32 s58, s3, 10
	v_readlane_b32 s18, v252, 26
	s_and_b32 s19, s84, 7
	s_cmp_lg_u32 s19, 0
	s_mov_b32 s0, s18
	s_cbranch_scc1 .Lat_item
	s_and_b32 s19, s18, 7
	s_lshr_b32 s0, s84, 3
	s_mul_i32 s0, s19, s0
	s_lshr_b32 s19, s18, 3
	s_add_u32 s0, s0, s19
.Lat_item:
	s_cmpk_gt_i32 s0, 0xff
	s_cbranch_scc1 .Lat_exit
	s_lshr_b32 s18, s0, 7
	s_bfe_u32 s19, s0, 0x30004
	v_readlane_b32 s4, v252, 35
	v_readlane_b32 s5, v252, 36
	v_readlane_b32 s6, v252, 37
	v_readlane_b32 s7, v252, 38
	s_mul_i32 s12, s18, 0x5960000
	s_lshl_b32 s19, s19, 7
	s_add_u32 s12, s12, s19
	s_add_u32 s4, s4, s12
	s_addc_u32 s5, s5, 0
	s_lshl_b32 s12, s18, 23
	s_add_u32 s6, s6, s12
	s_addc_u32 s7, s7, 0
	s_mov_b32 s1, 0
.Lat_unit:
	s_and_b32 s2, s0, 15
	s_cmp_eq_u32 s1, 0
	s_cbranch_scc1 .Lat_qb
	s_sub_u32 s2, 31, s2
.Lat_qb:
	s_lshl_b32 s9, s2, 2
	s_lshr_b32 s10, s3, 1
	s_add_u32 s10, s10, s9
	s_add_u32 s11, s9, 3
	s_add_u32 s9, s9, 4
	s_lshl_b32 s18, s2, 8
	s_lshl_b32 s19, s3, 5
	s_add_u32 s18, s18, s19
	v_and_b32_e32 v235, 31, v186
	v_bfe_u32 v237, v186, 5, 1
	v_add_u32_e32 v235, s18, v235
	v_lshlrev_b32_e32 v219, 10, v235
	v_mul_u32_u24_e32 v236, 0x2cb0, v235
	v_lshl_add_u32 v220, v237, 4, v236
	v_lshl_add_u32 v197, v237, 3, v236
	global_load_dwordx4 v[102:105], v220, s[4:5] offset:0
	global_load_dwordx4 v[106:109], v220, s[4:5] offset:32
	global_load_dwordx4 v[110:113], v220, s[4:5] offset:64
	global_load_dwordx4 v[114:117], v220, s[4:5] offset:96
	s_mov_b64 s[12:13], s[4:5]
	s_add_i32 m0, s58, 0x0
	s_nop 0
	global_load_lds_dwordx4 v221, s[12:13]
	s_add_i32 m0, s58, 0x8000
	s_nop 0
	global_load_lds_dwordx4 v222, s[12:13]
	s_add_u32 s12, s12, 0xb2c00
	s_addc_u32 s13, s13, 0
	s_add_i32 m0, s58, 0x2000
	s_nop 0
	global_load_lds_dwordx4 v221, s[12:13]
	s_add_u32 s12, s12, 0xb2c00
	s_addc_u32 s13, s13, 0
	s_add_i32 m0, s58, 0x4000
	s_nop 0
	global_load_lds_dwordx4 v221, s[12:13]
	s_add_u32 s12, s12, 0xb2c00
	s_addc_u32 s13, s13, 0
	global_load_dwordx2 v[214:215], v219, s[6:7]
	s_add_i32 m0, s58, 0x6000
	s_nop 0
	global_load_lds_dwordx4 v221, s[12:13]
	s_add_u32 s14, s4, 0xb2c00
	s_addc_u32 s15, s5, 0
	s_add_i32 m0, s58, 0xa000
	s_nop 0
	global_load_lds_dwordx4 v222, s[14:15]
	global_load_dwordx2 v[216:217], v219, s[6:7] offset:8
	v_mov_b32_e32 v230, 0xff800000
	v_mov_b32_e32 v231, 0
	v_mov_b32_e32 v0, 0
	v_mov_b32_e32 v1, 0
	v_mov_b32_e32 v2, 0
	v_mov_b32_e32 v3, 0
	v_mov_b32_e32 v4, 0
	v_mov_b32_e32 v5, 0
	v_mov_b32_e32 v6, 0
	v_mov_b32_e32 v7, 0
	v_mov_b32_e32 v8, 0
	v_mov_b32_e32 v9, 0
	v_mov_b32_e32 v10, 0
	v_mov_b32_e32 v11, 0
	v_mov_b32_e32 v12, 0
	v_mov_b32_e32 v13, 0
	v_mov_b32_e32 v14, 0
	v_mov_b32_e32 v15, 0
	v_mov_b32_e32 v16, 0
	v_mov_b32_e32 v17, 0
	v_mov_b32_e32 v18, 0
	v_mov_b32_e32 v19, 0
	v_mov_b32_e32 v20, 0
	v_mov_b32_e32 v21, 0
	v_mov_b32_e32 v22, 0
	v_mov_b32_e32 v23, 0
	v_mov_b32_e32 v24, 0
	v_mov_b32_e32 v25, 0
	v_mov_b32_e32 v26, 0
	v_mov_b32_e32 v27, 0
	v_mov_b32_e32 v28, 0
	v_mov_b32_e32 v29, 0
	v_mov_b32_e32 v30, 0
	v_mov_b32_e32 v31, 0
	s_waitcnt vmcnt(3)
	s_barrier
	ds_read_b128 v[118:121], v223 offset:0
	ds_read_b128 v[122:125], v223 offset:4096
	ds_read_b128 v[126:129], v224 offset:0
	ds_read_b128 v[130:133], v224 offset:4096
	ds_read_b128 v[134:137], v225 offset:0
	ds_read_b128 v[138:141], v225 offset:4096
	ds_read_b128 v[142:145], v226 offset:0
	ds_read_b128 v[146:149], v226 offset:4096
	s_waitcnt lgkmcnt(0)
	s_barrier
	v_mfma_f32_32x32x16_bf16 v[34:49], v[118:121], v[102:105], 0
	v_mfma_f32_32x32x16_bf16 v[50:65], v[122:125], v[102:105], 0
	v_mfma_f32_32x32x16_bf16 v[34:49], v[126:129], v[106:109], v[34:49]
	v_mfma_f32_32x32x16_bf16 v[50:65], v[130:133], v[106:109], v[50:65]
	v_mfma_f32_32x32x16_bf16 v[34:49], v[134:137], v[110:113], v[34:49]
	v_mfma_f32_32x32x16_bf16 v[50:65], v[138:141], v[110:113], v[50:65]
	v_mfma_f32_32x32x16_bf16 v[34:49], v[142:145], v[114:117], v[34:49]
	v_mfma_f32_32x32x16_bf16 v[50:65], v[146:149], v[114:117], v[50:65]
	ds_read_b128 v[118:121], v223 offset:8192
	ds_read_b128 v[122:125], v223 offset:12288
	ds_read_b128 v[126:129], v224 offset:8192
	ds_read_b128 v[130:133], v224 offset:12288
	ds_read_b128 v[134:137], v225 offset:8192
	ds_read_b128 v[138:141], v225 offset:12288
	ds_read_b128 v[142:145], v226 offset:8192
	ds_read_b128 v[146:149], v226 offset:12288
	s_waitcnt lgkmcnt(14)
	s_mov_b32 s8, 0
	s_nop 7
	v_lshrrev_b32_e32 v249, v229, v214
	v_lshrrev_b32_e32 v250, v229, v215
	v_bfe_i32 v235, v249, 0, 1
	v_bfe_i32 v236, v250, 0, 1
	v_bfe_i32 v237, v249, 1, 1
	v_bfe_i32 v238, v250, 1, 1
	v_bfe_i32 v239, v249, 2, 1
	v_bfe_i32 v240, v250, 2, 1
	v_bfe_i32 v241, v249, 3, 1
	v_bfe_i32 v242, v250, 3, 1
	v_bitop3_b32 v34, v34, s33, v235 bitop3:0xe4
	v_bitop3_b32 v50, v50, s33, v236 bitop3:0xe4
	v_bitop3_b32 v35, v35, s33, v237 bitop3:0xe4
	v_bitop3_b32 v51, v51, s33, v238 bitop3:0xe4
	v_bitop3_b32 v36, v36, s33, v239 bitop3:0xe4
	v_bitop3_b32 v52, v52, s33, v240 bitop3:0xe4
	v_bitop3_b32 v37, v37, s33, v241 bitop3:0xe4
	v_bitop3_b32 v53, v53, s33, v242 bitop3:0xe4
	v_max3_f32 v247, v34, s33, v50
	v_max3_f32 v248, v35, s33, v51
	v_max3_f32 v247, v247, v36, v52
	v_max3_f32 v248, v248, v37, v53
	v_bfe_i32 v235, v249, 8, 1
	v_bfe_i32 v236, v250, 8, 1
	v_bfe_i32 v237, v249, 9, 1
	v_bfe_i32 v238, v250, 9, 1
	v_bfe_i32 v239, v249, 10, 1
	v_bfe_i32 v240, v250, 10, 1
	v_bfe_i32 v241, v249, 11, 1
	v_bfe_i32 v242, v250, 11, 1
	v_bitop3_b32 v38, v38, s33, v235 bitop3:0xe4
	v_bitop3_b32 v54, v54, s33, v236 bitop3:0xe4
	v_bitop3_b32 v39, v39, s33, v237 bitop3:0xe4
	v_bitop3_b32 v55, v55, s33, v238 bitop3:0xe4
	v_bitop3_b32 v40, v40, s33, v239 bitop3:0xe4
	v_bitop3_b32 v56, v56, s33, v240 bitop3:0xe4
	v_bitop3_b32 v41, v41, s33, v241 bitop3:0xe4
	v_bitop3_b32 v57, v57, s33, v242 bitop3:0xe4
	v_max3_f32 v247, v247, v38, v54
	v_max3_f32 v248, v248, v39, v55
	v_max3_f32 v247, v247, v40, v56
	v_max3_f32 v248, v248, v41, v57
	v_bfe_i32 v235, v249, 16, 1
	v_bfe_i32 v236, v250, 16, 1
	v_bfe_i32 v237, v249, 17, 1
	v_bfe_i32 v238, v250, 17, 1
	v_bfe_i32 v239, v249, 18, 1
	v_bfe_i32 v240, v250, 18, 1
	v_bfe_i32 v241, v249, 19, 1
	v_bfe_i32 v242, v250, 19, 1
	v_bitop3_b32 v42, v42, s33, v235 bitop3:0xe4
	v_bitop3_b32 v58, v58, s33, v236 bitop3:0xe4
	v_bitop3_b32 v43, v43, s33, v237 bitop3:0xe4
	v_bitop3_b32 v59, v59, s33, v238 bitop3:0xe4
	v_bitop3_b32 v44, v44, s33, v239 bitop3:0xe4
	v_bitop3_b32 v60, v60, s33, v240 bitop3:0xe4
	v_bitop3_b32 v45, v45, s33, v241 bitop3:0xe4
	v_bitop3_b32 v61, v61, s33, v242 bitop3:0xe4
	v_max3_f32 v247, v247, v42, v58
	v_max3_f32 v248, v248, v43, v59
	v_max3_f32 v247, v247, v44, v60
	v_max3_f32 v248, v248, v45, v61
	v_bfe_i32 v235, v249, 24, 1
	v_bfe_i32 v236, v250, 24, 1
	v_bfe_i32 v237, v249, 25, 1
	v_bfe_i32 v238, v250, 25, 1
	v_bfe_i32 v239, v249, 26, 1
	v_bfe_i32 v240, v250, 26, 1
	v_bfe_i32 v241, v249, 27, 1
	v_bfe_i32 v242, v250, 27, 1
	v_bitop3_b32 v46, v46, s33, v235 bitop3:0xe4
	v_bitop3_b32 v62, v62, s33, v236 bitop3:0xe4
	v_bitop3_b32 v47, v47, s33, v237 bitop3:0xe4
	v_bitop3_b32 v63, v63, s33, v238 bitop3:0xe4
	v_bitop3_b32 v48, v48, s33, v239 bitop3:0xe4
	v_bitop3_b32 v64, v64, s33, v240 bitop3:0xe4
	v_bitop3_b32 v49, v49, s33, v241 bitop3:0xe4
	v_bitop3_b32 v65, v65, s33, v242 bitop3:0xe4
	v_max3_f32 v247, v247, v46, v62
	v_max3_f32 v248, v248, v47, v63
	v_max3_f32 v247, v247, v48, v64
	v_max3_f32 v248, v248, v49, v65
	v_max_f32_e32 v247, v247, v248
	v_mov_b32_e32 v248, v247
	s_nop 1
	v_permlane32_swap_b32_e32 v247, v248
	v_max3_f32 v247, v230, v247, v248
	v_cmp_neq_f32_e32 vcc, s33, v247
	s_nop 1
	v_cndmask_b32_e32 v248, 0, v247, vcc
	v_sub_f32_e32 v33, v230, v248
	v_mul_f32_e32 v33, 0x3e38aa3b, v33
	v_exp_f32_e32 v232, v33
	v_mul_f32_e32 v234, 0xbe38aa3b, v248
	v_mov_b32_e32 v230, v247
.Lat_loop_0:
	s_add_u32 s18, s8, 4
	s_min_u32 s18, s18, s11
	s_mul_i32 s18, s18, 0xb2c00
	s_add_u32 s12, s4, s18
	s_addc_u32 s13, s5, 0
	s_add_u32 s19, s8, 2
	s_min_u32 s19, s19, s11
	s_mul_i32 s18, s19, 0xb2c00
	s_add_u32 s14, s4, s18
	s_addc_u32 s15, s5, 0
	s_lshl_b32 s19, s19, 3
	s_add_u32 s16, s6, s19
	s_addc_u32 s17, s7, 0
	s_add_i32 m0, s58, 0x0
	s_nop 0
	global_load_lds_dwordx4 v221, s[12:13]
	s_add_i32 m0, s58, 0xc000
	s_nop 0
	global_load_lds_dwordx4 v222, s[14:15]
	global_load_dwordx2 v[214:215], v219, s[16:17]
	s_cmp_lt_u32 s8, s10
	s_cbranch_scc1 .Lat_full_0
	s_cmp_eq_u32 s8, s10
	s_cbranch_scc1 .Lat_last_0
.Lat_idle_0:
	s_waitcnt vmcnt(3)
	s_barrier
	s_add_u32 s8, s8, 1
	s_cmp_lt_u32 s8, s9
	s_cbranch_scc1 .Lat_loop_1
	s_branch .Lat_epilogue
.Lat_full_0:
	v_cmp_neq_f32_e32 vcc, 1.0, v232
	s_cbranch_vccz .Lat_nors_f0
	v_pk_mul_f32 v[0:1], v[0:1], v[232:233] op_sel_hi:[1,0]
	v_pk_mul_f32 v[2:3], v[2:3], v[232:233] op_sel_hi:[1,0]
	v_pk_mul_f32 v[4:5], v[4:5], v[232:233] op_sel_hi:[1,0]
	v_pk_mul_f32 v[6:7], v[6:7], v[232:233] op_sel_hi:[1,0]
	v_pk_mul_f32 v[8:9], v[8:9], v[232:233] op_sel_hi:[1,0]
	v_pk_mul_f32 v[10:11], v[10:11], v[232:233] op_sel_hi:[1,0]
	v_pk_mul_f32 v[12:13], v[12:13], v[232:233] op_sel_hi:[1,0]
	v_pk_mul_f32 v[14:15], v[14:15], v[232:233] op_sel_hi:[1,0]
	v_pk_mul_f32 v[16:17], v[16:17], v[232:233] op_sel_hi:[1,0]
	v_pk_mul_f32 v[18:19], v[18:19], v[232:233] op_sel_hi:[1,0]
	v_pk_mul_f32 v[20:21], v[20:21], v[232:233] op_sel_hi:[1,0]
	v_pk_mul_f32 v[22:23], v[22:23], v[232:233] op_sel_hi:[1,0]
	v_pk_mul_f32 v[24:25], v[24:25], v[232:233] op_sel_hi:[1,0]
	v_pk_mul_f32 v[26:27], v[26:27], v[232:233] op_sel_hi:[1,0]
	v_pk_mul_f32 v[28:29], v[28:29], v[232:233] op_sel_hi:[1,0]
	v_pk_mul_f32 v[30:31], v[30:31], v[232:233] op_sel_hi:[1,0]
.Lat_nors_f0:
	v_fmamk_f32 v34, v34, 0x3e38aa3b, v234
	v_fmamk_f32 v35, v35, 0x3e38aa3b, v234
	s_waitcnt lgkmcnt(7)
	v_mfma_f32_32x32x16_bf16 v[70:85], v[118:121], v[102:105], 0
	ds_read_b64_tr_b16 v[154:155], v227 offset:0
	ds_read_b64_tr_b16 v[156:157], v227 offset:1024
	v_fmamk_f32 v36, v36, 0x3e38aa3b, v234
	v_fmamk_f32 v37, v37, 0x3e38aa3b, v234
	v_fmamk_f32 v38, v38, 0x3e38aa3b, v234
	v_fmamk_f32 v39, v39, 0x3e38aa3b, v234
	v_fmamk_f32 v40, v40, 0x3e38aa3b, v234
	v_fmamk_f32 v41, v41, 0x3e38aa3b, v234
	v_exp_f32_e32 v34, v34
	v_exp_f32_e32 v35, v35
	v_exp_f32_e32 v36, v36
	v_exp_f32_e32 v37, v37
	v_exp_f32_e32 v38, v38
	v_exp_f32_e32 v39, v39
	s_waitcnt lgkmcnt(8)
	v_mfma_f32_32x32x16_bf16 v[86:101], v[122:125], v[102:105], 0
	ds_read_b64_tr_b16 v[158:159], v228 offset:0
	ds_read_b64_tr_b16 v[160:161], v228 offset:1024
	v_exp_f32_e32 v40, v40
	v_exp_f32_e32 v41, v41
	v_add_f32_e32 v243, v34, v38
	v_add_f32_e32 v244, v35, v39
	v_add_f32_e32 v245, v36, v40
	v_add_f32_e32 v246, v37, v41
	v_cvt_pk_bf16_f32 v34, v34, v35
	v_cvt_pk_bf16_f32 v35, v36, v37
	v_cvt_pk_bf16_f32 v36, v38, v39
	v_cvt_pk_bf16_f32 v37, v40, v41
	v_fmamk_f32 v42, v42, 0x3e38aa3b, v234
	v_fmamk_f32 v43, v43, 0x3e38aa3b, v234
	s_waitcnt lgkmcnt(9)
	v_mfma_f32_32x32x16_bf16 v[70:85], v[126:129], v[106:109], v[70:85]
	ds_read_b64_tr_b16 v[162:163], v227 offset:2048
	ds_read_b64_tr_b16 v[164:165], v227 offset:3072
	v_fmamk_f32 v44, v44, 0x3e38aa3b, v234
	v_fmamk_f32 v45, v45, 0x3e38aa3b, v234
	v_fmamk_f32 v46, v46, 0x3e38aa3b, v234
	v_fmamk_f32 v47, v47, 0x3e38aa3b, v234
	v_fmamk_f32 v48, v48, 0x3e38aa3b, v234
	v_fmamk_f32 v49, v49, 0x3e38aa3b, v234
	v_exp_f32_e32 v42, v42
	v_exp_f32_e32 v43, v43
	v_exp_f32_e32 v44, v44
	v_exp_f32_e32 v45, v45
	v_exp_f32_e32 v46, v46
	v_exp_f32_e32 v47, v47
	s_waitcnt lgkmcnt(10)
	v_mfma_f32_32x32x16_bf16 v[86:101], v[130:133], v[106:109], v[86:101]
	ds_read_b64_tr_b16 v[166:167], v228 offset:2048
	ds_read_b64_tr_b16 v[168:169], v228 offset:3072
	v_exp_f32_e32 v48, v48
	v_exp_f32_e32 v49, v49
	v_add_f32_e32 v243, v243, v42
	v_add_f32_e32 v244, v244, v43
	v_add_f32_e32 v245, v245, v44
	v_add_f32_e32 v246, v246, v45
	v_add_f32_e32 v243, v243, v46
	v_add_f32_e32 v244, v244, v47
	v_add_f32_e32 v245, v245, v48
	v_add_f32_e32 v246, v246, v49
	v_cvt_pk_bf16_f32 v42, v42, v43
	v_cvt_pk_bf16_f32 v43, v44, v45
	s_waitcnt lgkmcnt(11)
	v_mfma_f32_32x32x16_bf16 v[70:85], v[134:137], v[110:113], v[70:85]
	ds_read_b64_tr_b16 v[170:171], v227 offset:4096
	ds_read_b64_tr_b16 v[172:173], v227 offset:5120
	v_cvt_pk_bf16_f32 v44, v46, v47
	v_cvt_pk_bf16_f32 v45, v48, v49
	v_fmamk_f32 v50, v50, 0x3e38aa3b, v234
	v_fmamk_f32 v51, v51, 0x3e38aa3b, v234
	v_fmamk_f32 v52, v52, 0x3e38aa3b, v234
	v_fmamk_f32 v53, v53, 0x3e38aa3b, v234
	v_fmamk_f32 v54, v54, 0x3e38aa3b, v234
	v_fmamk_f32 v55, v55, 0x3e38aa3b, v234
	v_fmamk_f32 v56, v56, 0x3e38aa3b, v234
	v_fmamk_f32 v57, v57, 0x3e38aa3b, v234
	v_exp_f32_e32 v50, v50
	v_exp_f32_e32 v51, v51
	s_waitcnt lgkmcnt(12)
	v_mfma_f32_32x32x16_bf16 v[86:101], v[138:141], v[110:113], v[86:101]
	ds_read_b64_tr_b16 v[174:175], v228 offset:4096
	ds_read_b64_tr_b16 v[176:177], v228 offset:5120
	v_exp_f32_e32 v52, v52
	v_exp_f32_e32 v53, v53
	v_exp_f32_e32 v54, v54
	v_exp_f32_e32 v55, v55
	v_exp_f32_e32 v56, v56
	v_exp_f32_e32 v57, v57
	v_add_f32_e32 v243, v243, v50
	v_add_f32_e32 v244, v244, v51
	v_add_f32_e32 v245, v245, v52
	v_add_f32_e32 v246, v246, v53
	v_add_f32_e32 v243, v243, v54
	v_add_f32_e32 v244, v244, v55
	s_waitcnt lgkmcnt(13)
	v_mfma_f32_32x32x16_bf16 v[70:85], v[142:145], v[114:117], v[70:85]
	ds_read_b64_tr_b16 v[178:179], v227 offset:6144
	ds_read_b64_tr_b16 v[180:181], v227 offset:7168
	v_add_f32_e32 v245, v245, v56
	v_add_f32_e32 v246, v246, v57
	v_cvt_pk_bf16_f32 v50, v50, v51
	v_cvt_pk_bf16_f32 v51, v52, v53
	v_cvt_pk_bf16_f32 v52, v54, v55
	v_cvt_pk_bf16_f32 v53, v56, v57
	v_fmamk_f32 v58, v58, 0x3e38aa3b, v234
	v_fmamk_f32 v59, v59, 0x3e38aa3b, v234
	v_fmamk_f32 v60, v60, 0x3e38aa3b, v234
	v_fmamk_f32 v61, v61, 0x3e38aa3b, v234
	v_fmamk_f32 v62, v62, 0x3e38aa3b, v234
	v_fmamk_f32 v63, v63, 0x3e38aa3b, v234
	s_waitcnt lgkmcnt(14)
	v_mfma_f32_32x32x16_bf16 v[86:101], v[146:149], v[114:117], v[86:101]
	ds_read_b64_tr_b16 v[182:183], v228 offset:6144
	ds_read_b64_tr_b16 v[184:185], v228 offset:7168
	s_waitcnt lgkmcnt(14)
	v_fmamk_f32 v64, v64, 0x3e38aa3b, v234
	v_fmamk_f32 v65, v65, 0x3e38aa3b, v234
	v_exp_f32_e32 v58, v58
	v_exp_f32_e32 v59, v59
	v_exp_f32_e32 v60, v60
	v_exp_f32_e32 v61, v61
	v_exp_f32_e32 v62, v62
	v_exp_f32_e32 v63, v63
	v_exp_f32_e32 v64, v64
	v_exp_f32_e32 v65, v65
	v_add_f32_e32 v243, v243, v58
	v_add_f32_e32 v244, v244, v59
	v_add_f32_e32 v245, v245, v60
	v_add_f32_e32 v246, v246, v61
	s_waitcnt lgkmcnt(14)
	v_mfma_f32_32x32x16_bf16 v[0:15], v[154:157], v[34:37], v[0:15]
	ds_read_b128 v[118:121], v223 offset:16384
	v_add_f32_e32 v243, v243, v62
	v_add_f32_e32 v244, v244, v63
	v_add_f32_e32 v245, v245, v64
	v_add_f32_e32 v246, v246, v65
	v_cvt_pk_bf16_f32 v58, v58, v59
	v_cvt_pk_bf16_f32 v59, v60, v61
	v_cvt_pk_bf16_f32 v60, v62, v63
	v_cvt_pk_bf16_f32 v61, v64, v65
	v_add_f32_e32 v243, v243, v244
	v_add_f32_e32 v245, v245, v246
	v_add_f32_e32 v243, v243, v245
	v_fma_f32 v231, v231, v232, v243
	s_waitcnt lgkmcnt(13)
	v_mfma_f32_32x32x16_bf16 v[16:31], v[158:161], v[34:37], v[16:31]
	ds_read_b128 v[122:125], v223 offset:20480
	s_waitcnt vmcnt(3)
	v_lshrrev_b32_e32 v249, v229, v216
	v_lshrrev_b32_e32 v250, v229, v217
	v_bfe_i32 v235, v249, 0, 1
	v_bfe_i32 v236, v250, 0, 1
	v_bfe_i32 v237, v249, 1, 1
	v_bfe_i32 v238, v250, 1, 1
	v_bfe_i32 v239, v249, 2, 1
	v_bfe_i32 v240, v250, 2, 1
	v_bfe_i32 v241, v249, 3, 1
	v_bfe_i32 v242, v250, 3, 1
	v_bitop3_b32 v70, v70, s33, v235 bitop3:0xe4
	s_waitcnt lgkmcnt(12)
	v_mfma_f32_32x32x16_bf16 v[0:15], v[162:165], v[42:45], v[0:15]
	ds_read_b128 v[126:129], v224 offset:16384
	v_bitop3_b32 v86, v86, s33, v236 bitop3:0xe4
	v_bitop3_b32 v71, v71, s33, v237 bitop3:0xe4
	v_bitop3_b32 v87, v87, s33, v238 bitop3:0xe4
	v_bitop3_b32 v72, v72, s33, v239 bitop3:0xe4
	v_bitop3_b32 v88, v88, s33, v240 bitop3:0xe4
	v_bitop3_b32 v73, v73, s33, v241 bitop3:0xe4
	v_bitop3_b32 v89, v89, s33, v242 bitop3:0xe4
	v_max3_f32 v247, v70, s33, v86
	v_max3_f32 v248, v71, s33, v87
	v_max3_f32 v247, v247, v72, v88
	v_max3_f32 v248, v248, v73, v89
	v_bfe_i32 v235, v249, 8, 1
	s_waitcnt lgkmcnt(11)
	v_mfma_f32_32x32x16_bf16 v[16:31], v[166:169], v[42:45], v[16:31]
	ds_read_b128 v[130:133], v224 offset:20480
	v_bfe_i32 v236, v250, 8, 1
	v_bfe_i32 v237, v249, 9, 1
	v_bfe_i32 v238, v250, 9, 1
	v_bfe_i32 v239, v249, 10, 1
	v_bfe_i32 v240, v250, 10, 1
	v_bfe_i32 v241, v249, 11, 1
	v_bfe_i32 v242, v250, 11, 1
	v_bitop3_b32 v74, v74, s33, v235 bitop3:0xe4
	v_bitop3_b32 v90, v90, s33, v236 bitop3:0xe4
	v_bitop3_b32 v75, v75, s33, v237 bitop3:0xe4
	v_bitop3_b32 v91, v91, s33, v238 bitop3:0xe4
	v_bitop3_b32 v76, v76, s33, v239 bitop3:0xe4
	s_waitcnt lgkmcnt(10)
	v_mfma_f32_32x32x16_bf16 v[0:15], v[170:173], v[50:53], v[0:15]
	ds_read_b128 v[134:137], v225 offset:16384
	v_bitop3_b32 v92, v92, s33, v240 bitop3:0xe4
	v_bitop3_b32 v77, v77, s33, v241 bitop3:0xe4
	v_bitop3_b32 v93, v93, s33, v242 bitop3:0xe4
	v_max3_f32 v247, v247, v74, v90
	v_max3_f32 v248, v248, v75, v91
	v_max3_f32 v247, v247, v76, v92
	v_max3_f32 v248, v248, v77, v93
	v_bfe_i32 v235, v249, 16, 1
	v_bfe_i32 v236, v250, 16, 1
	v_bfe_i32 v237, v249, 17, 1
	v_bfe_i32 v238, v250, 17, 1
	v_bfe_i32 v239, v249, 18, 1
	s_waitcnt lgkmcnt(9)
	v_mfma_f32_32x32x16_bf16 v[16:31], v[174:177], v[50:53], v[16:31]
	ds_read_b128 v[138:141], v225 offset:20480
	v_bfe_i32 v240, v250, 18, 1
	v_bfe_i32 v241, v249, 19, 1
	v_bfe_i32 v242, v250, 19, 1
	v_bitop3_b32 v78, v78, s33, v235 bitop3:0xe4
	v_bitop3_b32 v94, v94, s33, v236 bitop3:0xe4
	v_bitop3_b32 v79, v79, s33, v237 bitop3:0xe4
	v_bitop3_b32 v95, v95, s33, v238 bitop3:0xe4
	v_bitop3_b32 v80, v80, s33, v239 bitop3:0xe4
	v_bitop3_b32 v96, v96, s33, v240 bitop3:0xe4
	v_bitop3_b32 v81, v81, s33, v241 bitop3:0xe4
	v_bitop3_b32 v97, v97, s33, v242 bitop3:0xe4
	v_max3_f32 v247, v247, v78, v94
	s_waitcnt lgkmcnt(8)
	v_mfma_f32_32x32x16_bf16 v[0:15], v[178:181], v[58:61], v[0:15]
	ds_read_b128 v[142:145], v226 offset:16384
	v_max3_f32 v248, v248, v79, v95
	v_max3_f32 v247, v247, v80, v96
	v_max3_f32 v248, v248, v81, v97
	v_bfe_i32 v235, v249, 24, 1
	v_bfe_i32 v236, v250, 24, 1
	v_bfe_i32 v237, v249, 25, 1
	v_bfe_i32 v238, v250, 25, 1
	v_bfe_i32 v239, v249, 26, 1
	v_bfe_i32 v240, v250, 26, 1
	v_bfe_i32 v241, v249, 27, 1
	v_bfe_i32 v242, v250, 27, 1
	v_bitop3_b32 v82, v82, s33, v235 bitop3:0xe4
	s_waitcnt lgkmcnt(7)
	v_mfma_f32_32x32x16_bf16 v[16:31], v[182:185], v[58:61], v[16:31]
	ds_read_b128 v[146:149], v226 offset:20480
	v_bitop3_b32 v98, v98, s33, v236 bitop3:0xe4
	v_bitop3_b32 v83, v83, s33, v237 bitop3:0xe4
	v_bitop3_b32 v99, v99, s33, v238 bitop3:0xe4
	v_bitop3_b32 v84, v84, s33, v239 bitop3:0xe4
	v_bitop3_b32 v100, v100, s33, v240 bitop3:0xe4
	v_bitop3_b32 v85, v85, s33, v241 bitop3:0xe4
	v_bitop3_b32 v101, v101, s33, v242 bitop3:0xe4
	v_max3_f32 v247, v247, v82, v98
	v_max3_f32 v248, v248, v83, v99
	v_max3_f32 v247, v247, v84, v100
	v_max3_f32 v248, v248, v85, v101
	v_max_f32_e32 v247, v247, v248
	v_mov_b32_e32 v248, v247
	s_nop 1
	v_permlane32_swap_b32_e32 v247, v248
	v_max3_f32 v247, v230, v247, v248
	v_cmp_neq_f32_e32 vcc, s33, v247
	s_nop 1
	v_cndmask_b32_e32 v248, 0, v247, vcc
	v_sub_f32_e32 v33, v230, v248
	v_mul_f32_e32 v33, 0x3e38aa3b, v33
	v_exp_f32_e32 v232, v33
	v_mul_f32_e32 v234, 0xbe38aa3b, v248
	v_mov_b32_e32 v230, v247
	s_waitcnt vmcnt(3)
	s_barrier
	s_add_u32 s8, s8, 1
	s_cmp_lt_u32 s8, s9
	s_cbranch_scc1 .Lat_loop_1
	s_branch .Lat_epilogue
.Lat_last_0:
	ds_read_b64_tr_b16 v[154:155], v227 offset:0
	ds_read_b64_tr_b16 v[156:157], v227 offset:1024
	ds_read_b64_tr_b16 v[158:159], v228 offset:0
	ds_read_b64_tr_b16 v[160:161], v228 offset:1024
	ds_read_b64_tr_b16 v[162:163], v227 offset:2048
	ds_read_b64_tr_b16 v[164:165], v227 offset:3072
	ds_read_b64_tr_b16 v[166:167], v228 offset:2048
	v_cmp_neq_f32_e32 vcc, 1.0, v232
	s_cbranch_vccz .Lat_nors_l0
	v_pk_mul_f32 v[0:1], v[0:1], v[232:233] op_sel_hi:[1,0]
	v_pk_mul_f32 v[2:3], v[2:3], v[232:233] op_sel_hi:[1,0]
	v_pk_mul_f32 v[4:5], v[4:5], v[232:233] op_sel_hi:[1,0]
	v_pk_mul_f32 v[6:7], v[6:7], v[232:233] op_sel_hi:[1,0]
	v_pk_mul_f32 v[8:9], v[8:9], v[232:233] op_sel_hi:[1,0]
	v_pk_mul_f32 v[10:11], v[10:11], v[232:233] op_sel_hi:[1,0]
	v_pk_mul_f32 v[12:13], v[12:13], v[232:233] op_sel_hi:[1,0]
	v_pk_mul_f32 v[14:15], v[14:15], v[232:233] op_sel_hi:[1,0]
	v_pk_mul_f32 v[16:17], v[16:17], v[232:233] op_sel_hi:[1,0]
	v_pk_mul_f32 v[18:19], v[18:19], v[232:233] op_sel_hi:[1,0]
	v_pk_mul_f32 v[20:21], v[20:21], v[232:233] op_sel_hi:[1,0]
	v_pk_mul_f32 v[22:23], v[22:23], v[232:233] op_sel_hi:[1,0]
	v_pk_mul_f32 v[24:25], v[24:25], v[232:233] op_sel_hi:[1,0]
	v_pk_mul_f32 v[26:27], v[26:27], v[232:233] op_sel_hi:[1,0]
	v_pk_mul_f32 v[28:29], v[28:29], v[232:233] op_sel_hi:[1,0]
	v_pk_mul_f32 v[30:31], v[30:31], v[232:233] op_sel_hi:[1,0]
.Lat_nors_l0:
	v_fmamk_f32 v34, v34, 0x3e38aa3b, v234
	v_fmamk_f32 v35, v35, 0x3e38aa3b, v234
	v_fmamk_f32 v36, v36, 0x3e38aa3b, v234
	ds_read_b64_tr_b16 v[168:169], v228 offset:3072
	s_waitcnt lgkmcnt(14)
	v_fmamk_f32 v37, v37, 0x3e38aa3b, v234
	v_fmamk_f32 v38, v38, 0x3e38aa3b, v234
	v_fmamk_f32 v39, v39, 0x3e38aa3b, v234
	ds_read_b64_tr_b16 v[170:171], v227 offset:4096
	s_waitcnt lgkmcnt(14)
	v_fmamk_f32 v40, v40, 0x3e38aa3b, v234
	v_fmamk_f32 v41, v41, 0x3e38aa3b, v234
	v_exp_f32_e32 v34, v34
	ds_read_b64_tr_b16 v[172:173], v227 offset:5120
	s_waitcnt lgkmcnt(14)
	v_exp_f32_e32 v35, v35
	v_exp_f32_e32 v36, v36
	v_exp_f32_e32 v37, v37
	ds_read_b64_tr_b16 v[174:175], v228 offset:4096
	s_waitcnt lgkmcnt(14)
	v_exp_f32_e32 v38, v38
	v_exp_f32_e32 v39, v39
	v_exp_f32_e32 v40, v40
	ds_read_b64_tr_b16 v[176:177], v228 offset:5120
	s_waitcnt lgkmcnt(14)
	v_exp_f32_e32 v41, v41
	v_add_f32_e32 v243, v34, v38
	v_add_f32_e32 v244, v35, v39
	ds_read_b64_tr_b16 v[178:179], v227 offset:6144
	s_waitcnt lgkmcnt(14)
	v_add_f32_e32 v245, v36, v40
	v_add_f32_e32 v246, v37, v41
	v_cvt_pk_bf16_f32 v34, v34, v35
	ds_read_b64_tr_b16 v[180:181], v227 offset:7168
	s_waitcnt lgkmcnt(14)
	v_cvt_pk_bf16_f32 v35, v36, v37
	v_cvt_pk_bf16_f32 v36, v38, v39
	v_cvt_pk_bf16_f32 v37, v40, v41
	ds_read_b64_tr_b16 v[182:183], v228 offset:6144
	s_waitcnt lgkmcnt(14)
	s_waitcnt lgkmcnt(13)
	v_mfma_f32_32x32x16_bf16 v[0:15], v[154:157], v[34:37], v[0:15]
	s_waitcnt lgkmcnt(11)
	v_mfma_f32_32x32x16_bf16 v[16:31], v[158:161], v[34:37], v[16:31]
	v_fmamk_f32 v42, v42, 0x3e38aa3b, v234
	v_fmamk_f32 v43, v43, 0x3e38aa3b, v234
	v_fmamk_f32 v44, v44, 0x3e38aa3b, v234
	ds_read_b64_tr_b16 v[184:185], v228 offset:7168
	v_fmamk_f32 v45, v45, 0x3e38aa3b, v234
	v_fmamk_f32 v46, v46, 0x3e38aa3b, v234
	v_fmamk_f32 v47, v47, 0x3e38aa3b, v234
	v_fmamk_f32 v48, v48, 0x3e38aa3b, v234
	v_fmamk_f32 v49, v49, 0x3e38aa3b, v234
	v_exp_f32_e32 v42, v42
	v_exp_f32_e32 v43, v43
	v_exp_f32_e32 v44, v44
	v_exp_f32_e32 v45, v45
	v_exp_f32_e32 v46, v46
	v_exp_f32_e32 v47, v47
	v_exp_f32_e32 v48, v48
	v_exp_f32_e32 v49, v49
	v_add_f32_e32 v243, v243, v42
	v_add_f32_e32 v244, v244, v43
	v_add_f32_e32 v245, v245, v44
	v_add_f32_e32 v246, v246, v45
	v_add_f32_e32 v243, v243, v46
	v_add_f32_e32 v244, v244, v47
	v_add_f32_e32 v245, v245, v48
	v_add_f32_e32 v246, v246, v49
	v_cvt_pk_bf16_f32 v42, v42, v43
	v_cvt_pk_bf16_f32 v43, v44, v45
	v_cvt_pk_bf16_f32 v44, v46, v47
	v_cvt_pk_bf16_f32 v45, v48, v49
	s_waitcnt lgkmcnt(10)
	v_mfma_f32_32x32x16_bf16 v[0:15], v[162:165], v[42:45], v[0:15]
	s_waitcnt lgkmcnt(8)
	v_mfma_f32_32x32x16_bf16 v[16:31], v[166:169], v[42:45], v[16:31]
	v_fmamk_f32 v50, v50, 0x3e38aa3b, v234
	v_fmamk_f32 v51, v51, 0x3e38aa3b, v234
	v_fmamk_f32 v52, v52, 0x3e38aa3b, v234
	v_fmamk_f32 v53, v53, 0x3e38aa3b, v234
	v_fmamk_f32 v54, v54, 0x3e38aa3b, v234
	v_fmamk_f32 v55, v55, 0x3e38aa3b, v234
	v_fmamk_f32 v56, v56, 0x3e38aa3b, v234
	v_fmamk_f32 v57, v57, 0x3e38aa3b, v234
	v_exp_f32_e32 v50, v50
	v_exp_f32_e32 v51, v51
	v_exp_f32_e32 v52, v52
	v_exp_f32_e32 v53, v53
	v_exp_f32_e32 v54, v54
	v_exp_f32_e32 v55, v55
	v_exp_f32_e32 v56, v56
	v_exp_f32_e32 v57, v57
	v_add_f32_e32 v243, v243, v50
	v_add_f32_e32 v244, v244, v51
	v_add_f32_e32 v245, v245, v52
	v_add_f32_e32 v246, v246, v53
	v_add_f32_e32 v243, v243, v54
	v_add_f32_e32 v244, v244, v55
	v_add_f32_e32 v245, v245, v56
	v_add_f32_e32 v246, v246, v57
	v_cvt_pk_bf16_f32 v50, v50, v51
	v_cvt_pk_bf16_f32 v51, v52, v53
	v_cvt_pk_bf16_f32 v52, v54, v55
	v_cvt_pk_bf16_f32 v53, v56, v57
	s_waitcnt lgkmcnt(6)
	v_mfma_f32_32x32x16_bf16 v[0:15], v[170:173], v[50:53], v[0:15]
	s_waitcnt lgkmcnt(4)
	v_mfma_f32_32x32x16_bf16 v[16:31], v[174:177], v[50:53], v[16:31]
	v_fmamk_f32 v58, v58, 0x3e38aa3b, v234
	v_fmamk_f32 v59, v59, 0x3e38aa3b, v234
	v_fmamk_f32 v60, v60, 0x3e38aa3b, v234
	v_fmamk_f32 v61, v61, 0x3e38aa3b, v234
	v_fmamk_f32 v62, v62, 0x3e38aa3b, v234
	v_fmamk_f32 v63, v63, 0x3e38aa3b, v234
	v_fmamk_f32 v64, v64, 0x3e38aa3b, v234
	v_fmamk_f32 v65, v65, 0x3e38aa3b, v234
	v_exp_f32_e32 v58, v58
	v_exp_f32_e32 v59, v59
	v_exp_f32_e32 v60, v60
	v_exp_f32_e32 v61, v61
	v_exp_f32_e32 v62, v62
	v_exp_f32_e32 v63, v63
	v_exp_f32_e32 v64, v64
	v_exp_f32_e32 v65, v65
	v_add_f32_e32 v243, v243, v58
	v_add_f32_e32 v244, v244, v59
	v_add_f32_e32 v245, v245, v60
	v_add_f32_e32 v246, v246, v61
	v_add_f32_e32 v243, v243, v62
	v_add_f32_e32 v244, v244, v63
	v_add_f32_e32 v245, v245, v64
	v_add_f32_e32 v246, v246, v65
	v_cvt_pk_bf16_f32 v58, v58, v59
	v_cvt_pk_bf16_f32 v59, v60, v61
	v_cvt_pk_bf16_f32 v60, v62, v63
	v_cvt_pk_bf16_f32 v61, v64, v65
	v_add_f32_e32 v243, v243, v244
	v_add_f32_e32 v245, v245, v246
	v_add_f32_e32 v243, v243, v245
	v_fma_f32 v231, v231, v232, v243
	s_waitcnt lgkmcnt(2)
	v_mfma_f32_32x32x16_bf16 v[0:15], v[178:181], v[58:61], v[0:15]
	s_waitcnt lgkmcnt(0)
	v_mfma_f32_32x32x16_bf16 v[16:31], v[182:185], v[58:61], v[16:31]
	s_waitcnt vmcnt(3)
	s_barrier
	s_add_u32 s8, s8, 1
	s_cmp_lt_u32 s8, s9
	s_cbranch_scc1 .Lat_loop_1
	s_branch .Lat_epilogue
.Lat_loop_1:
	s_add_u32 s18, s8, 4
	s_min_u32 s18, s18, s11
	s_mul_i32 s18, s18, 0xb2c00
	s_add_u32 s12, s4, s18
	s_addc_u32 s13, s5, 0
	s_add_u32 s19, s8, 2
	s_min_u32 s19, s19, s11
	s_mul_i32 s18, s19, 0xb2c00
	s_add_u32 s14, s4, s18
	s_addc_u32 s15, s5, 0
	s_lshl_b32 s19, s19, 3
	s_add_u32 s16, s6, s19
	s_addc_u32 s17, s7, 0
	s_add_i32 m0, s58, 0x2000
	s_nop 0
	global_load_lds_dwordx4 v221, s[12:13]
	s_add_i32 m0, s58, 0xe000
	s_nop 0
	global_load_lds_dwordx4 v222, s[14:15]
	global_load_dwordx2 v[216:217], v219, s[16:17]
	s_cmp_lt_u32 s8, s10
	s_cbranch_scc1 .Lat_full_1
	s_cmp_eq_u32 s8, s10
	s_cbranch_scc1 .Lat_last_1

.Lat_nors_f1:
	v_fmamk_f32 v70, v70, 0x3e38aa3b, v234
	v_fmamk_f32 v71, v71, 0x3e38aa3b, v234
	s_waitcnt lgkmcnt(7)
	v_mfma_f32_32x32x16_bf16 v[34:49], v[118:121], v[102:105], 0
	ds_read_b64_tr_b16 v[154:155], v227 offset:8192
	ds_read_b64_tr_b16 v[156:157], v227 offset:9216
	v_fmamk_f32 v72, v72, 0x3e38aa3b, v234
	v_fmamk_f32 v73, v73, 0x3e38aa3b, v234
	v_fmamk_f32 v74, v74, 0x3e38aa3b, v234
	v_fmamk_f32 v75, v75, 0x3e38aa3b, v234
	v_fmamk_f32 v76, v76, 0x3e38aa3b, v234
	v_fmamk_f32 v77, v77, 0x3e38aa3b, v234
	v_exp_f32_e32 v70, v70
	v_exp_f32_e32 v71, v71
	v_exp_f32_e32 v72, v72
	v_exp_f32_e32 v73, v73
	v_exp_f32_e32 v74, v74
	v_exp_f32_e32 v75, v75
	s_waitcnt lgkmcnt(8)
	v_mfma_f32_32x32x16_bf16 v[50:65], v[122:125], v[102:105], 0
	ds_read_b64_tr_b16 v[158:159], v228 offset:8192
	ds_read_b64_tr_b16 v[160:161], v228 offset:9216
	v_exp_f32_e32 v76, v76
	v_exp_f32_e32 v77, v77
	v_add_f32_e32 v243, v70, v74
	v_add_f32_e32 v244, v71, v75
	v_add_f32_e32 v245, v72, v76
	v_add_f32_e32 v246, v73, v77
	v_cvt_pk_bf16_f32 v70, v70, v71
	v_cvt_pk_bf16_f32 v71, v72, v73
	v_cvt_pk_bf16_f32 v72, v74, v75
	v_cvt_pk_bf16_f32 v73, v76, v77
	v_fmamk_f32 v78, v78, 0x3e38aa3b, v234
	v_fmamk_f32 v79, v79, 0x3e38aa3b, v234
	s_waitcnt lgkmcnt(9)
	v_mfma_f32_32x32x16_bf16 v[34:49], v[126:129], v[106:109], v[34:49]
	ds_read_b64_tr_b16 v[162:163], v227 offset:10240
	ds_read_b64_tr_b16 v[164:165], v227 offset:11264
	v_fmamk_f32 v80, v80, 0x3e38aa3b, v234
	v_fmamk_f32 v81, v81, 0x3e38aa3b, v234
	v_fmamk_f32 v82, v82, 0x3e38aa3b, v234
	v_fmamk_f32 v83, v83, 0x3e38aa3b, v234
	v_fmamk_f32 v84, v84, 0x3e38aa3b, v234
	v_fmamk_f32 v85, v85, 0x3e38aa3b, v234
	v_exp_f32_e32 v78, v78
	v_exp_f32_e32 v79, v79
	v_exp_f32_e32 v80, v80
	v_exp_f32_e32 v81, v81
	v_exp_f32_e32 v82, v82
	v_exp_f32_e32 v83, v83
	s_waitcnt lgkmcnt(10)
	v_mfma_f32_32x32x16_bf16 v[50:65], v[130:133], v[106:109], v[50:65]
	ds_read_b64_tr_b16 v[166:167], v228 offset:10240
	ds_read_b64_tr_b16 v[168:169], v228 offset:11264
	v_exp_f32_e32 v84, v84
	v_exp_f32_e32 v85, v85
	v_add_f32_e32 v243, v243, v78
	v_add_f32_e32 v244, v244, v79
	v_add_f32_e32 v245, v245, v80
	v_add_f32_e32 v246, v246, v81
	v_add_f32_e32 v243, v243, v82
	v_add_f32_e32 v244, v244, v83
	v_add_f32_e32 v245, v245, v84
	v_add_f32_e32 v246, v246, v85
	v_cvt_pk_bf16_f32 v78, v78, v79
	v_cvt_pk_bf16_f32 v79, v80, v81
	s_waitcnt lgkmcnt(11)
	v_mfma_f32_32x32x16_bf16 v[34:49], v[134:137], v[110:113], v[34:49]
	ds_read_b64_tr_b16 v[170:171], v227 offset:12288
	ds_read_b64_tr_b16 v[172:173], v227 offset:13312
	v_cvt_pk_bf16_f32 v80, v82, v83
	v_cvt_pk_bf16_f32 v81, v84, v85
	v_fmamk_f32 v86, v86, 0x3e38aa3b, v234
	v_fmamk_f32 v87, v87, 0x3e38aa3b, v234
	v_fmamk_f32 v88, v88, 0x3e38aa3b, v234
	v_fmamk_f32 v89, v89, 0x3e38aa3b, v234
	v_fmamk_f32 v90, v90, 0x3e38aa3b, v234
	v_fmamk_f32 v91, v91, 0x3e38aa3b, v234
	v_fmamk_f32 v92, v92, 0x3e38aa3b, v234
	v_fmamk_f32 v93, v93, 0x3e38aa3b, v234
	v_exp_f32_e32 v86, v86
	v_exp_f32_e32 v87, v87
	s_waitcnt lgkmcnt(12)
	v_mfma_f32_32x32x16_bf16 v[50:65], v[138:141], v[110:113], v[50:65]
	ds_read_b64_tr_b16 v[174:175], v228 offset:12288
	ds_read_b64_tr_b16 v[176:177], v228 offset:13312
	v_exp_f32_e32 v88, v88
	v_exp_f32_e32 v89, v89
	v_exp_f32_e32 v90, v90
	v_exp_f32_e32 v91, v91
	v_exp_f32_e32 v92, v92
	v_exp_f32_e32 v93, v93
	v_add_f32_e32 v243, v243, v86
	v_add_f32_e32 v244, v244, v87
	v_add_f32_e32 v245, v245, v88
	v_add_f32_e32 v246, v246, v89
	v_add_f32_e32 v243, v243, v90
	v_add_f32_e32 v244, v244, v91
	s_waitcnt lgkmcnt(13)
	v_mfma_f32_32x32x16_bf16 v[34:49], v[142:145], v[114:117], v[34:49]
	ds_read_b64_tr_b16 v[178:179], v227 offset:14336
	ds_read_b64_tr_b16 v[180:181], v227 offset:15360
	v_add_f32_e32 v245, v245, v92
	v_add_f32_e32 v246, v246, v93
	v_cvt_pk_bf16_f32 v86, v86, v87
	v_cvt_pk_bf16_f32 v87, v88, v89
	v_cvt_pk_bf16_f32 v88, v90, v91
	v_cvt_pk_bf16_f32 v89, v92, v93
	v_fmamk_f32 v94, v94, 0x3e38aa3b, v234
	v_fmamk_f32 v95, v95, 0x3e38aa3b, v234
	v_fmamk_f32 v96, v96, 0x3e38aa3b, v234
	v_fmamk_f32 v97, v97, 0x3e38aa3b, v234
	v_fmamk_f32 v98, v98, 0x3e38aa3b, v234
	v_fmamk_f32 v99, v99, 0x3e38aa3b, v234
	s_waitcnt lgkmcnt(14)
	v_mfma_f32_32x32x16_bf16 v[50:65], v[146:149], v[114:117], v[50:65]
	ds_read_b64_tr_b16 v[182:183], v228 offset:14336
	ds_read_b64_tr_b16 v[184:185], v228 offset:15360
	s_waitcnt lgkmcnt(14)
	v_fmamk_f32 v100, v100, 0x3e38aa3b, v234
	v_fmamk_f32 v101, v101, 0x3e38aa3b, v234
	v_exp_f32_e32 v94, v94
	v_exp_f32_e32 v95, v95
	v_exp_f32_e32 v96, v96
	v_exp_f32_e32 v97, v97
	v_exp_f32_e32 v98, v98
	v_exp_f32_e32 v99, v99
	v_exp_f32_e32 v100, v100
	v_exp_f32_e32 v101, v101
	v_add_f32_e32 v243, v243, v94
	v_add_f32_e32 v244, v244, v95
	v_add_f32_e32 v245, v245, v96
	v_add_f32_e32 v246, v246, v97
	s_waitcnt lgkmcnt(14)
	v_mfma_f32_32x32x16_bf16 v[0:15], v[154:157], v[70:73], v[0:15]
	ds_read_b128 v[118:121], v223 offset:24576
	v_add_f32_e32 v243, v243, v98
	v_add_f32_e32 v244, v244, v99
	v_add_f32_e32 v245, v245, v100
	v_add_f32_e32 v246, v246, v101
	v_cvt_pk_bf16_f32 v94, v94, v95
	v_cvt_pk_bf16_f32 v95, v96, v97
	v_cvt_pk_bf16_f32 v96, v98, v99
	v_cvt_pk_bf16_f32 v97, v100, v101
	v_add_f32_e32 v243, v243, v244
	v_add_f32_e32 v245, v245, v246
	v_add_f32_e32 v243, v243, v245
	v_fma_f32 v231, v231, v232, v243
	s_waitcnt lgkmcnt(13)
	v_mfma_f32_32x32x16_bf16 v[16:31], v[158:161], v[70:73], v[16:31]
	ds_read_b128 v[122:125], v223 offset:28672
	s_waitcnt vmcnt(3)
	v_lshrrev_b32_e32 v249, v229, v214
	v_lshrrev_b32_e32 v250, v229, v215
	v_bfe_i32 v235, v249, 0, 1
	v_bfe_i32 v236, v250, 0, 1
	v_bfe_i32 v237, v249, 1, 1
	v_bfe_i32 v238, v250, 1, 1
	v_bfe_i32 v239, v249, 2, 1
	v_bfe_i32 v240, v250, 2, 1
	v_bfe_i32 v241, v249, 3, 1
	v_bfe_i32 v242, v250, 3, 1
	v_bitop3_b32 v34, v34, s33, v235 bitop3:0xe4
	s_waitcnt lgkmcnt(12)
	v_mfma_f32_32x32x16_bf16 v[0:15], v[162:165], v[78:81], v[0:15]
	ds_read_b128 v[126:129], v224 offset:24576
	v_bitop3_b32 v50, v50, s33, v236 bitop3:0xe4
	v_bitop3_b32 v35, v35, s33, v237 bitop3:0xe4
	v_bitop3_b32 v51, v51, s33, v238 bitop3:0xe4
	v_bitop3_b32 v36, v36, s33, v239 bitop3:0xe4
	v_bitop3_b32 v52, v52, s33, v240 bitop3:0xe4
	v_bitop3_b32 v37, v37, s33, v241 bitop3:0xe4
	v_bitop3_b32 v53, v53, s33, v242 bitop3:0xe4
	v_max3_f32 v247, v34, s33, v50
	v_max3_f32 v248, v35, s33, v51
	v_max3_f32 v247, v247, v36, v52
	v_max3_f32 v248, v248, v37, v53
	v_bfe_i32 v235, v249, 8, 1
	s_waitcnt lgkmcnt(11)
	v_mfma_f32_32x32x16_bf16 v[16:31], v[166:169], v[78:81], v[16:31]
	ds_read_b128 v[130:133], v224 offset:28672
	v_bfe_i32 v236, v250, 8, 1
	v_bfe_i32 v237, v249, 9, 1
	v_bfe_i32 v238, v250, 9, 1
	v_bfe_i32 v239, v249, 10, 1
	v_bfe_i32 v240, v250, 10, 1
	v_bfe_i32 v241, v249, 11, 1
	v_bfe_i32 v242, v250, 11, 1
	v_bitop3_b32 v38, v38, s33, v235 bitop3:0xe4
	v_bitop3_b32 v54, v54, s33, v236 bitop3:0xe4
	v_bitop3_b32 v39, v39, s33, v237 bitop3:0xe4
	v_bitop3_b32 v55, v55, s33, v238 bitop3:0xe4
	v_bitop3_b32 v40, v40, s33, v239 bitop3:0xe4
	s_waitcnt lgkmcnt(10)
	v_mfma_f32_32x32x16_bf16 v[0:15], v[170:173], v[86:89], v[0:15]
	ds_read_b128 v[134:137], v225 offset:24576
	v_bitop3_b32 v56, v56, s33, v240 bitop3:0xe4
	v_bitop3_b32 v41, v41, s33, v241 bitop3:0xe4
	v_bitop3_b32 v57, v57, s33, v242 bitop3:0xe4
	v_max3_f32 v247, v247, v38, v54
	v_max3_f32 v248, v248, v39, v55
	v_max3_f32 v247, v247, v40, v56
	v_max3_f32 v248, v248, v41, v57
	v_bfe_i32 v235, v249, 16, 1
	v_bfe_i32 v236, v250, 16, 1
	v_bfe_i32 v237, v249, 17, 1
	v_bfe_i32 v238, v250, 17, 1
	v_bfe_i32 v239, v249, 18, 1
	s_waitcnt lgkmcnt(9)
	v_mfma_f32_32x32x16_bf16 v[16:31], v[174:177], v[86:89], v[16:31]
	ds_read_b128 v[138:141], v225 offset:28672
	v_bfe_i32 v240, v250, 18, 1
	v_bfe_i32 v241, v249, 19, 1
	v_bfe_i32 v242, v250, 19, 1
	v_bitop3_b32 v42, v42, s33, v235 bitop3:0xe4
	v_bitop3_b32 v58, v58, s33, v236 bitop3:0xe4
	v_bitop3_b32 v43, v43, s33, v237 bitop3:0xe4
	v_bitop3_b32 v59, v59, s33, v238 bitop3:0xe4
	v_bitop3_b32 v44, v44, s33, v239 bitop3:0xe4
	v_bitop3_b32 v60, v60, s33, v240 bitop3:0xe4
	v_bitop3_b32 v45, v45, s33, v241 bitop3:0xe4
	v_bitop3_b32 v61, v61, s33, v242 bitop3:0xe4
	v_max3_f32 v247, v247, v42, v58
	s_waitcnt lgkmcnt(8)
	v_mfma_f32_32x32x16_bf16 v[0:15], v[178:181], v[94:97], v[0:15]
	ds_read_b128 v[142:145], v226 offset:24576
	v_max3_f32 v248, v248, v43, v59
	v_max3_f32 v247, v247, v44, v60
	v_max3_f32 v248, v248, v45, v61
	v_bfe_i32 v235, v249, 24, 1
	v_bfe_i32 v236, v250, 24, 1
	v_bfe_i32 v237, v249, 25, 1
	v_bfe_i32 v238, v250, 25, 1
	v_bfe_i32 v239, v249, 26, 1
	v_bfe_i32 v240, v250, 26, 1
	v_bfe_i32 v241, v249, 27, 1
	v_bfe_i32 v242, v250, 27, 1
	v_bitop3_b32 v46, v46, s33, v235 bitop3:0xe4
	s_waitcnt lgkmcnt(7)
	v_mfma_f32_32x32x16_bf16 v[16:31], v[182:185], v[94:97], v[16:31]
	ds_read_b128 v[146:149], v226 offset:28672
	v_bitop3_b32 v62, v62, s33, v236 bitop3:0xe4
	v_bitop3_b32 v47, v47, s33, v237 bitop3:0xe4
	v_bitop3_b32 v63, v63, s33, v238 bitop3:0xe4
	v_bitop3_b32 v48, v48, s33, v239 bitop3:0xe4
	v_bitop3_b32 v64, v64, s33, v240 bitop3:0xe4
	v_bitop3_b32 v49, v49, s33, v241 bitop3:0xe4
	v_bitop3_b32 v65, v65, s33, v242 bitop3:0xe4
	v_max3_f32 v247, v247, v46, v62
	v_max3_f32 v248, v248, v47, v63
	v_max3_f32 v247, v247, v48, v64
	v_max3_f32 v248, v248, v49, v65
	v_max_f32_e32 v247, v247, v248
	v_mov_b32_e32 v248, v247
	s_nop 1
	v_permlane32_swap_b32_e32 v247, v248
	v_max3_f32 v247, v230, v247, v248
	v_cmp_neq_f32_e32 vcc, s33, v247
	s_nop 1
	v_cndmask_b32_e32 v248, 0, v247, vcc
	v_sub_f32_e32 v33, v230, v248
	v_mul_f32_e32 v33, 0x3e38aa3b, v33
	v_exp_f32_e32 v232, v33
	v_mul_f32_e32 v234, 0xbe38aa3b, v248
	v_mov_b32_e32 v230, v247
	s_waitcnt vmcnt(3)
	s_barrier
	s_add_u32 s8, s8, 1
	s_cmp_lt_u32 s8, s9
	s_cbranch_scc1 .Lat_loop_2
	s_branch .Lat_epilogue
.Lat_last_1:
	ds_read_b64_tr_b16 v[154:155], v227 offset:8192
	ds_read_b64_tr_b16 v[156:157], v227 offset:9216
	ds_read_b64_tr_b16 v[158:159], v228 offset:8192
	ds_read_b64_tr_b16 v[160:161], v228 offset:9216
	ds_read_b64_tr_b16 v[162:163], v227 offset:10240
	ds_read_b64_tr_b16 v[164:165], v227 offset:11264
	ds_read_b64_tr_b16 v[166:167], v228 offset:10240
	v_cmp_neq_f32_e32 vcc, 1.0, v232
	s_cbranch_vccz .Lat_nors_l1
	v_pk_mul_f32 v[0:1], v[0:1], v[232:233] op_sel_hi:[1,0]
	v_pk_mul_f32 v[2:3], v[2:3], v[232:233] op_sel_hi:[1,0]
	v_pk_mul_f32 v[4:5], v[4:5], v[232:233] op_sel_hi:[1,0]
	v_pk_mul_f32 v[6:7], v[6:7], v[232:233] op_sel_hi:[1,0]
	v_pk_mul_f32 v[8:9], v[8:9], v[232:233] op_sel_hi:[1,0]
	v_pk_mul_f32 v[10:11], v[10:11], v[232:233] op_sel_hi:[1,0]
	v_pk_mul_f32 v[12:13], v[12:13], v[232:233] op_sel_hi:[1,0]
	v_pk_mul_f32 v[14:15], v[14:15], v[232:233] op_sel_hi:[1,0]
	v_pk_mul_f32 v[16:17], v[16:17], v[232:233] op_sel_hi:[1,0]
	v_pk_mul_f32 v[18:19], v[18:19], v[232:233] op_sel_hi:[1,0]
	v_pk_mul_f32 v[20:21], v[20:21], v[232:233] op_sel_hi:[1,0]
	v_pk_mul_f32 v[22:23], v[22:23], v[232:233] op_sel_hi:[1,0]
	v_pk_mul_f32 v[24:25], v[24:25], v[232:233] op_sel_hi:[1,0]
	v_pk_mul_f32 v[26:27], v[26:27], v[232:233] op_sel_hi:[1,0]
	v_pk_mul_f32 v[28:29], v[28:29], v[232:233] op_sel_hi:[1,0]
	v_pk_mul_f32 v[30:31], v[30:31], v[232:233] op_sel_hi:[1,0]
.Lat_nors_l1:
	v_fmamk_f32 v70, v70, 0x3e38aa3b, v234
	v_fmamk_f32 v71, v71, 0x3e38aa3b, v234
	v_fmamk_f32 v72, v72, 0x3e38aa3b, v234
	ds_read_b64_tr_b16 v[168:169], v228 offset:11264
	s_waitcnt lgkmcnt(14)
	v_fmamk_f32 v73, v73, 0x3e38aa3b, v234
	v_fmamk_f32 v74, v74, 0x3e38aa3b, v234
	v_fmamk_f32 v75, v75, 0x3e38aa3b, v234
	ds_read_b64_tr_b16 v[170:171], v227 offset:12288
	s_waitcnt lgkmcnt(14)
	v_fmamk_f32 v76, v76, 0x3e38aa3b, v234
	v_fmamk_f32 v77, v77, 0x3e38aa3b, v234
	v_exp_f32_e32 v70, v70
	ds_read_b64_tr_b16 v[172:173], v227 offset:13312
	s_waitcnt lgkmcnt(14)
	v_exp_f32_e32 v71, v71
	v_exp_f32_e32 v72, v72
	v_exp_f32_e32 v73, v73
	ds_read_b64_tr_b16 v[174:175], v228 offset:12288
	s_waitcnt lgkmcnt(14)
	v_exp_f32_e32 v74, v74
	v_exp_f32_e32 v75, v75
	v_exp_f32_e32 v76, v76
	ds_read_b64_tr_b16 v[176:177], v228 offset:13312
	s_waitcnt lgkmcnt(14)
	v_exp_f32_e32 v77, v77
	v_add_f32_e32 v243, v70, v74
	v_add_f32_e32 v244, v71, v75
	ds_read_b64_tr_b16 v[178:179], v227 offset:14336
	s_waitcnt lgkmcnt(14)
	v_add_f32_e32 v245, v72, v76
	v_add_f32_e32 v246, v73, v77
	v_cvt_pk_bf16_f32 v70, v70, v71
	ds_read_b64_tr_b16 v[180:181], v227 offset:15360
	s_waitcnt lgkmcnt(14)
	v_cvt_pk_bf16_f32 v71, v72, v73
	v_cvt_pk_bf16_f32 v72, v74, v75
	v_cvt_pk_bf16_f32 v73, v76, v77
	ds_read_b64_tr_b16 v[182:183], v228 offset:14336
	s_waitcnt lgkmcnt(14)
	s_waitcnt lgkmcnt(13)
	v_mfma_f32_32x32x16_bf16 v[0:15], v[154:157], v[70:73], v[0:15]
	s_waitcnt lgkmcnt(11)
	v_mfma_f32_32x32x16_bf16 v[16:31], v[158:161], v[70:73], v[16:31]
	v_fmamk_f32 v78, v78, 0x3e38aa3b, v234
	v_fmamk_f32 v79, v79, 0x3e38aa3b, v234
	v_fmamk_f32 v80, v80, 0x3e38aa3b, v234
	ds_read_b64_tr_b16 v[184:185], v228 offset:15360
	v_fmamk_f32 v81, v81, 0x3e38aa3b, v234
	v_fmamk_f32 v82, v82, 0x3e38aa3b, v234
	v_fmamk_f32 v83, v83, 0x3e38aa3b, v234
	v_fmamk_f32 v84, v84, 0x3e38aa3b, v234
	v_fmamk_f32 v85, v85, 0x3e38aa3b, v234
	v_exp_f32_e32 v78, v78
	v_exp_f32_e32 v79, v79
	v_exp_f32_e32 v80, v80
	v_exp_f32_e32 v81, v81
	v_exp_f32_e32 v82, v82
	v_exp_f32_e32 v83, v83
	v_exp_f32_e32 v84, v84
	v_exp_f32_e32 v85, v85
	v_add_f32_e32 v243, v243, v78
	v_add_f32_e32 v244, v244, v79
	v_add_f32_e32 v245, v245, v80
	v_add_f32_e32 v246, v246, v81
	v_add_f32_e32 v243, v243, v82
	v_add_f32_e32 v244, v244, v83
	v_add_f32_e32 v245, v245, v84
	v_add_f32_e32 v246, v246, v85
	v_cvt_pk_bf16_f32 v78, v78, v79
	v_cvt_pk_bf16_f32 v79, v80, v81
	v_cvt_pk_bf16_f32 v80, v82, v83
	v_cvt_pk_bf16_f32 v81, v84, v85
	s_waitcnt lgkmcnt(10)
	v_mfma_f32_32x32x16_bf16 v[0:15], v[162:165], v[78:81], v[0:15]
	s_waitcnt lgkmcnt(8)
	v_mfma_f32_32x32x16_bf16 v[16:31], v[166:169], v[78:81], v[16:31]
	v_fmamk_f32 v86, v86, 0x3e38aa3b, v234
	v_fmamk_f32 v87, v87, 0x3e38aa3b, v234
	v_fmamk_f32 v88, v88, 0x3e38aa3b, v234
	v_fmamk_f32 v89, v89, 0x3e38aa3b, v234
	v_fmamk_f32 v90, v90, 0x3e38aa3b, v234
	v_fmamk_f32 v91, v91, 0x3e38aa3b, v234
	v_fmamk_f32 v92, v92, 0x3e38aa3b, v234
	v_fmamk_f32 v93, v93, 0x3e38aa3b, v234
	v_exp_f32_e32 v86, v86
	v_exp_f32_e32 v87, v87
	v_exp_f32_e32 v88, v88
	v_exp_f32_e32 v89, v89
	v_exp_f32_e32 v90, v90
	v_exp_f32_e32 v91, v91
	v_exp_f32_e32 v92, v92
	v_exp_f32_e32 v93, v93
	v_add_f32_e32 v243, v243, v86
	v_add_f32_e32 v244, v244, v87
	v_add_f32_e32 v245, v245, v88
	v_add_f32_e32 v246, v246, v89
	v_add_f32_e32 v243, v243, v90
	v_add_f32_e32 v244, v244, v91
	v_add_f32_e32 v245, v245, v92
	v_add_f32_e32 v246, v246, v93
	v_cvt_pk_bf16_f32 v86, v86, v87
	v_cvt_pk_bf16_f32 v87, v88, v89
	v_cvt_pk_bf16_f32 v88, v90, v91
	v_cvt_pk_bf16_f32 v89, v92, v93
	s_waitcnt lgkmcnt(6)
	v_mfma_f32_32x32x16_bf16 v[0:15], v[170:173], v[86:89], v[0:15]
	s_waitcnt lgkmcnt(4)
	v_mfma_f32_32x32x16_bf16 v[16:31], v[174:177], v[86:89], v[16:31]
	v_fmamk_f32 v94, v94, 0x3e38aa3b, v234
	v_fmamk_f32 v95, v95, 0x3e38aa3b, v234
	v_fmamk_f32 v96, v96, 0x3e38aa3b, v234
	v_fmamk_f32 v97, v97, 0x3e38aa3b, v234
	v_fmamk_f32 v98, v98, 0x3e38aa3b, v234
	v_fmamk_f32 v99, v99, 0x3e38aa3b, v234
	v_fmamk_f32 v100, v100, 0x3e38aa3b, v234
	v_fmamk_f32 v101, v101, 0x3e38aa3b, v234
	v_exp_f32_e32 v94, v94
	v_exp_f32_e32 v95, v95
	v_exp_f32_e32 v96, v96
	v_exp_f32_e32 v97, v97
	v_exp_f32_e32 v98, v98
	v_exp_f32_e32 v99, v99
	v_exp_f32_e32 v100, v100
	v_exp_f32_e32 v101, v101
	v_add_f32_e32 v243, v243, v94
	v_add_f32_e32 v244, v244, v95
	v_add_f32_e32 v245, v245, v96
	v_add_f32_e32 v246, v246, v97
	v_add_f32_e32 v243, v243, v98
	v_add_f32_e32 v244, v244, v99
	v_add_f32_e32 v245, v245, v100
	v_add_f32_e32 v246, v246, v101
	v_cvt_pk_bf16_f32 v94, v94, v95
	v_cvt_pk_bf16_f32 v95, v96, v97
	v_cvt_pk_bf16_f32 v96, v98, v99
	v_cvt_pk_bf16_f32 v97, v100, v101
	v_add_f32_e32 v243, v243, v244
	v_add_f32_e32 v245, v245, v246
	v_add_f32_e32 v243, v243, v245
	v_fma_f32 v231, v231, v232, v243
	s_waitcnt lgkmcnt(2)
	v_mfma_f32_32x32x16_bf16 v[0:15], v[178:181], v[94:97], v[0:15]
	s_waitcnt lgkmcnt(0)
	v_mfma_f32_32x32x16_bf16 v[16:31], v[182:185], v[94:97], v[16:31]
	s_waitcnt vmcnt(3)
	s_barrier
	s_add_u32 s8, s8, 1
	s_cmp_lt_u32 s8, s9
	s_cbranch_scc1 .Lat_loop_2
	s_branch .Lat_epilogue
.Lat_loop_2:
	s_add_u32 s18, s8, 4
	s_min_u32 s18, s18, s11
	s_mul_i32 s18, s18, 0xb2c00
	s_add_u32 s12, s4, s18
	s_addc_u32 s13, s5, 0
	s_add_u32 s19, s8, 2
	s_min_u32 s19, s19, s11
	s_mul_i32 s18, s19, 0xb2c00
	s_add_u32 s14, s4, s18
	s_addc_u32 s15, s5, 0
	s_lshl_b32 s19, s19, 3
	s_add_u32 s16, s6, s19
	s_addc_u32 s17, s7, 0
	s_add_i32 m0, s58, 0x4000
	s_nop 0
	global_load_lds_dwordx4 v221, s[12:13]
	s_add_i32 m0, s58, 0x8000
	s_nop 0
	global_load_lds_dwordx4 v222, s[14:15]
	global_load_dwordx2 v[214:215], v219, s[16:17]
	s_cmp_lt_u32 s8, s10
	s_cbranch_scc1 .Lat_full_2
	s_cmp_eq_u32 s8, s10
	s_cbranch_scc1 .Lat_last_2

.Lat_nors_f2:
	v_fmamk_f32 v34, v34, 0x3e38aa3b, v234
	v_fmamk_f32 v35, v35, 0x3e38aa3b, v234
	s_waitcnt lgkmcnt(7)
	v_mfma_f32_32x32x16_bf16 v[70:85], v[118:121], v[102:105], 0
	ds_read_b64_tr_b16 v[154:155], v227 offset:16384
	ds_read_b64_tr_b16 v[156:157], v227 offset:17408
	v_fmamk_f32 v36, v36, 0x3e38aa3b, v234
	v_fmamk_f32 v37, v37, 0x3e38aa3b, v234
	v_fmamk_f32 v38, v38, 0x3e38aa3b, v234
	v_fmamk_f32 v39, v39, 0x3e38aa3b, v234
	v_fmamk_f32 v40, v40, 0x3e38aa3b, v234
	v_fmamk_f32 v41, v41, 0x3e38aa3b, v234
	v_exp_f32_e32 v34, v34
	v_exp_f32_e32 v35, v35
	v_exp_f32_e32 v36, v36
	v_exp_f32_e32 v37, v37
	v_exp_f32_e32 v38, v38
	v_exp_f32_e32 v39, v39
	s_waitcnt lgkmcnt(8)
	v_mfma_f32_32x32x16_bf16 v[86:101], v[122:125], v[102:105], 0
	ds_read_b64_tr_b16 v[158:159], v228 offset:16384
	ds_read_b64_tr_b16 v[160:161], v228 offset:17408
	v_exp_f32_e32 v40, v40
	v_exp_f32_e32 v41, v41
	v_add_f32_e32 v243, v34, v38
	v_add_f32_e32 v244, v35, v39
	v_add_f32_e32 v245, v36, v40
	v_add_f32_e32 v246, v37, v41
	v_cvt_pk_bf16_f32 v34, v34, v35
	v_cvt_pk_bf16_f32 v35, v36, v37
	v_cvt_pk_bf16_f32 v36, v38, v39
	v_cvt_pk_bf16_f32 v37, v40, v41
	v_fmamk_f32 v42, v42, 0x3e38aa3b, v234
	v_fmamk_f32 v43, v43, 0x3e38aa3b, v234
	s_waitcnt lgkmcnt(9)
	v_mfma_f32_32x32x16_bf16 v[70:85], v[126:129], v[106:109], v[70:85]
	ds_read_b64_tr_b16 v[162:163], v227 offset:18432
	ds_read_b64_tr_b16 v[164:165], v227 offset:19456
	v_fmamk_f32 v44, v44, 0x3e38aa3b, v234
	v_fmamk_f32 v45, v45, 0x3e38aa3b, v234
	v_fmamk_f32 v46, v46, 0x3e38aa3b, v234
	v_fmamk_f32 v47, v47, 0x3e38aa3b, v234
	v_fmamk_f32 v48, v48, 0x3e38aa3b, v234
	v_fmamk_f32 v49, v49, 0x3e38aa3b, v234
	v_exp_f32_e32 v42, v42
	v_exp_f32_e32 v43, v43
	v_exp_f32_e32 v44, v44
	v_exp_f32_e32 v45, v45
	v_exp_f32_e32 v46, v46
	v_exp_f32_e32 v47, v47
	s_waitcnt lgkmcnt(10)
	v_mfma_f32_32x32x16_bf16 v[86:101], v[130:133], v[106:109], v[86:101]
	ds_read_b64_tr_b16 v[166:167], v228 offset:18432
	ds_read_b64_tr_b16 v[168:169], v228 offset:19456
	v_exp_f32_e32 v48, v48
	v_exp_f32_e32 v49, v49
	v_add_f32_e32 v243, v243, v42
	v_add_f32_e32 v244, v244, v43
	v_add_f32_e32 v245, v245, v44
	v_add_f32_e32 v246, v246, v45
	v_add_f32_e32 v243, v243, v46
	v_add_f32_e32 v244, v244, v47
	v_add_f32_e32 v245, v245, v48
	v_add_f32_e32 v246, v246, v49
	v_cvt_pk_bf16_f32 v42, v42, v43
	v_cvt_pk_bf16_f32 v43, v44, v45
	s_waitcnt lgkmcnt(11)
	v_mfma_f32_32x32x16_bf16 v[70:85], v[134:137], v[110:113], v[70:85]
	ds_read_b64_tr_b16 v[170:171], v227 offset:20480
	ds_read_b64_tr_b16 v[172:173], v227 offset:21504
	v_cvt_pk_bf16_f32 v44, v46, v47
	v_cvt_pk_bf16_f32 v45, v48, v49
	v_fmamk_f32 v50, v50, 0x3e38aa3b, v234
	v_fmamk_f32 v51, v51, 0x3e38aa3b, v234
	v_fmamk_f32 v52, v52, 0x3e38aa3b, v234
	v_fmamk_f32 v53, v53, 0x3e38aa3b, v234
	v_fmamk_f32 v54, v54, 0x3e38aa3b, v234
	v_fmamk_f32 v55, v55, 0x3e38aa3b, v234
	v_fmamk_f32 v56, v56, 0x3e38aa3b, v234
	v_fmamk_f32 v57, v57, 0x3e38aa3b, v234
	v_exp_f32_e32 v50, v50
	v_exp_f32_e32 v51, v51
	s_waitcnt lgkmcnt(12)
	v_mfma_f32_32x32x16_bf16 v[86:101], v[138:141], v[110:113], v[86:101]
	ds_read_b64_tr_b16 v[174:175], v228 offset:20480
	ds_read_b64_tr_b16 v[176:177], v228 offset:21504
	v_exp_f32_e32 v52, v52
	v_exp_f32_e32 v53, v53
	v_exp_f32_e32 v54, v54
	v_exp_f32_e32 v55, v55
	v_exp_f32_e32 v56, v56
	v_exp_f32_e32 v57, v57
	v_add_f32_e32 v243, v243, v50
	v_add_f32_e32 v244, v244, v51
	v_add_f32_e32 v245, v245, v52
	v_add_f32_e32 v246, v246, v53
	v_add_f32_e32 v243, v243, v54
	v_add_f32_e32 v244, v244, v55
	s_waitcnt lgkmcnt(13)
	v_mfma_f32_32x32x16_bf16 v[70:85], v[142:145], v[114:117], v[70:85]
	ds_read_b64_tr_b16 v[178:179], v227 offset:22528
	ds_read_b64_tr_b16 v[180:181], v227 offset:23552
	v_add_f32_e32 v245, v245, v56
	v_add_f32_e32 v246, v246, v57
	v_cvt_pk_bf16_f32 v50, v50, v51
	v_cvt_pk_bf16_f32 v51, v52, v53
	v_cvt_pk_bf16_f32 v52, v54, v55
	v_cvt_pk_bf16_f32 v53, v56, v57
	v_fmamk_f32 v58, v58, 0x3e38aa3b, v234
	v_fmamk_f32 v59, v59, 0x3e38aa3b, v234
	v_fmamk_f32 v60, v60, 0x3e38aa3b, v234
	v_fmamk_f32 v61, v61, 0x3e38aa3b, v234
	v_fmamk_f32 v62, v62, 0x3e38aa3b, v234
	v_fmamk_f32 v63, v63, 0x3e38aa3b, v234
	s_waitcnt lgkmcnt(14)
	v_mfma_f32_32x32x16_bf16 v[86:101], v[146:149], v[114:117], v[86:101]
	ds_read_b64_tr_b16 v[182:183], v228 offset:22528
	ds_read_b64_tr_b16 v[184:185], v228 offset:23552
	s_waitcnt lgkmcnt(14)
	v_fmamk_f32 v64, v64, 0x3e38aa3b, v234
	v_fmamk_f32 v65, v65, 0x3e38aa3b, v234
	v_exp_f32_e32 v58, v58
	v_exp_f32_e32 v59, v59
	v_exp_f32_e32 v60, v60
	v_exp_f32_e32 v61, v61
	v_exp_f32_e32 v62, v62
	v_exp_f32_e32 v63, v63
	v_exp_f32_e32 v64, v64
	v_exp_f32_e32 v65, v65
	v_add_f32_e32 v243, v243, v58
	v_add_f32_e32 v244, v244, v59
	v_add_f32_e32 v245, v245, v60
	v_add_f32_e32 v246, v246, v61
	s_waitcnt lgkmcnt(14)
	v_mfma_f32_32x32x16_bf16 v[0:15], v[154:157], v[34:37], v[0:15]
	ds_read_b128 v[118:121], v223 offset:0
	v_add_f32_e32 v243, v243, v62
	v_add_f32_e32 v244, v244, v63
	v_add_f32_e32 v245, v245, v64
	v_add_f32_e32 v246, v246, v65
	v_cvt_pk_bf16_f32 v58, v58, v59
	v_cvt_pk_bf16_f32 v59, v60, v61
	v_cvt_pk_bf16_f32 v60, v62, v63
	v_cvt_pk_bf16_f32 v61, v64, v65
	v_add_f32_e32 v243, v243, v244
	v_add_f32_e32 v245, v245, v246
	v_add_f32_e32 v243, v243, v245
	v_fma_f32 v231, v231, v232, v243
	s_waitcnt lgkmcnt(13)
	v_mfma_f32_32x32x16_bf16 v[16:31], v[158:161], v[34:37], v[16:31]
	ds_read_b128 v[122:125], v223 offset:4096
	s_waitcnt vmcnt(3)
	v_lshrrev_b32_e32 v249, v229, v216
	v_lshrrev_b32_e32 v250, v229, v217
	v_bfe_i32 v235, v249, 0, 1
	v_bfe_i32 v236, v250, 0, 1
	v_bfe_i32 v237, v249, 1, 1
	v_bfe_i32 v238, v250, 1, 1
	v_bfe_i32 v239, v249, 2, 1
	v_bfe_i32 v240, v250, 2, 1
	v_bfe_i32 v241, v249, 3, 1
	v_bfe_i32 v242, v250, 3, 1
	v_bitop3_b32 v70, v70, s33, v235 bitop3:0xe4
	s_waitcnt lgkmcnt(12)
	v_mfma_f32_32x32x16_bf16 v[0:15], v[162:165], v[42:45], v[0:15]
	ds_read_b128 v[126:129], v224 offset:0
	v_bitop3_b32 v86, v86, s33, v236 bitop3:0xe4
	v_bitop3_b32 v71, v71, s33, v237 bitop3:0xe4
	v_bitop3_b32 v87, v87, s33, v238 bitop3:0xe4
	v_bitop3_b32 v72, v72, s33, v239 bitop3:0xe4
	v_bitop3_b32 v88, v88, s33, v240 bitop3:0xe4
	v_bitop3_b32 v73, v73, s33, v241 bitop3:0xe4
	v_bitop3_b32 v89, v89, s33, v242 bitop3:0xe4
	v_max3_f32 v247, v70, s33, v86
	v_max3_f32 v248, v71, s33, v87
	v_max3_f32 v247, v247, v72, v88
	v_max3_f32 v248, v248, v73, v89
	v_bfe_i32 v235, v249, 8, 1
	s_waitcnt lgkmcnt(11)
	v_mfma_f32_32x32x16_bf16 v[16:31], v[166:169], v[42:45], v[16:31]
	ds_read_b128 v[130:133], v224 offset:4096
	v_bfe_i32 v236, v250, 8, 1
	v_bfe_i32 v237, v249, 9, 1
	v_bfe_i32 v238, v250, 9, 1
	v_bfe_i32 v239, v249, 10, 1
	v_bfe_i32 v240, v250, 10, 1
	v_bfe_i32 v241, v249, 11, 1
	v_bfe_i32 v242, v250, 11, 1
	v_bitop3_b32 v74, v74, s33, v235 bitop3:0xe4
	v_bitop3_b32 v90, v90, s33, v236 bitop3:0xe4
	v_bitop3_b32 v75, v75, s33, v237 bitop3:0xe4
	v_bitop3_b32 v91, v91, s33, v238 bitop3:0xe4
	v_bitop3_b32 v76, v76, s33, v239 bitop3:0xe4
	s_waitcnt lgkmcnt(10)
	v_mfma_f32_32x32x16_bf16 v[0:15], v[170:173], v[50:53], v[0:15]
	ds_read_b128 v[134:137], v225 offset:0
	v_bitop3_b32 v92, v92, s33, v240 bitop3:0xe4
	v_bitop3_b32 v77, v77, s33, v241 bitop3:0xe4
	v_bitop3_b32 v93, v93, s33, v242 bitop3:0xe4
	v_max3_f32 v247, v247, v74, v90
	v_max3_f32 v248, v248, v75, v91
	v_max3_f32 v247, v247, v76, v92
	v_max3_f32 v248, v248, v77, v93
	v_bfe_i32 v235, v249, 16, 1
	v_bfe_i32 v236, v250, 16, 1
	v_bfe_i32 v237, v249, 17, 1
	v_bfe_i32 v238, v250, 17, 1
	v_bfe_i32 v239, v249, 18, 1
	s_waitcnt lgkmcnt(9)
	v_mfma_f32_32x32x16_bf16 v[16:31], v[174:177], v[50:53], v[16:31]
	ds_read_b128 v[138:141], v225 offset:4096
	v_bfe_i32 v240, v250, 18, 1
	v_bfe_i32 v241, v249, 19, 1
	v_bfe_i32 v242, v250, 19, 1
	v_bitop3_b32 v78, v78, s33, v235 bitop3:0xe4
	v_bitop3_b32 v94, v94, s33, v236 bitop3:0xe4
	v_bitop3_b32 v79, v79, s33, v237 bitop3:0xe4
	v_bitop3_b32 v95, v95, s33, v238 bitop3:0xe4
	v_bitop3_b32 v80, v80, s33, v239 bitop3:0xe4
	v_bitop3_b32 v96, v96, s33, v240 bitop3:0xe4
	v_bitop3_b32 v81, v81, s33, v241 bitop3:0xe4
	v_bitop3_b32 v97, v97, s33, v242 bitop3:0xe4
	v_max3_f32 v247, v247, v78, v94
	s_waitcnt lgkmcnt(8)
	v_mfma_f32_32x32x16_bf16 v[0:15], v[178:181], v[58:61], v[0:15]
	ds_read_b128 v[142:145], v226 offset:0
	v_max3_f32 v248, v248, v79, v95
	v_max3_f32 v247, v247, v80, v96
	v_max3_f32 v248, v248, v81, v97
	v_bfe_i32 v235, v249, 24, 1
	v_bfe_i32 v236, v250, 24, 1
	v_bfe_i32 v237, v249, 25, 1
	v_bfe_i32 v238, v250, 25, 1
	v_bfe_i32 v239, v249, 26, 1
	v_bfe_i32 v240, v250, 26, 1
	v_bfe_i32 v241, v249, 27, 1
	v_bfe_i32 v242, v250, 27, 1
	v_bitop3_b32 v82, v82, s33, v235 bitop3:0xe4
	s_waitcnt lgkmcnt(7)
	v_mfma_f32_32x32x16_bf16 v[16:31], v[182:185], v[58:61], v[16:31]
	ds_read_b128 v[146:149], v226 offset:4096
	v_bitop3_b32 v98, v98, s33, v236 bitop3:0xe4
	v_bitop3_b32 v83, v83, s33, v237 bitop3:0xe4
	v_bitop3_b32 v99, v99, s33, v238 bitop3:0xe4
	v_bitop3_b32 v84, v84, s33, v239 bitop3:0xe4
	v_bitop3_b32 v100, v100, s33, v240 bitop3:0xe4
	v_bitop3_b32 v85, v85, s33, v241 bitop3:0xe4
	v_bitop3_b32 v101, v101, s33, v242 bitop3:0xe4
	v_max3_f32 v247, v247, v82, v98
	v_max3_f32 v248, v248, v83, v99
	v_max3_f32 v247, v247, v84, v100
	v_max3_f32 v248, v248, v85, v101
	v_max_f32_e32 v247, v247, v248
	v_mov_b32_e32 v248, v247
	s_nop 1
	v_permlane32_swap_b32_e32 v247, v248
	v_max3_f32 v247, v230, v247, v248
	v_cmp_neq_f32_e32 vcc, s33, v247
	s_nop 1
	v_cndmask_b32_e32 v248, 0, v247, vcc
	v_sub_f32_e32 v33, v230, v248
	v_mul_f32_e32 v33, 0x3e38aa3b, v33
	v_exp_f32_e32 v232, v33
	v_mul_f32_e32 v234, 0xbe38aa3b, v248
	v_mov_b32_e32 v230, v247
	s_waitcnt vmcnt(3)
	s_barrier
	s_add_u32 s8, s8, 1
	s_cmp_lt_u32 s8, s9
	s_cbranch_scc1 .Lat_loop_3
	s_branch .Lat_epilogue
.Lat_last_2:
	ds_read_b64_tr_b16 v[154:155], v227 offset:16384
	ds_read_b64_tr_b16 v[156:157], v227 offset:17408
	ds_read_b64_tr_b16 v[158:159], v228 offset:16384
	ds_read_b64_tr_b16 v[160:161], v228 offset:17408
	ds_read_b64_tr_b16 v[162:163], v227 offset:18432
	ds_read_b64_tr_b16 v[164:165], v227 offset:19456
	ds_read_b64_tr_b16 v[166:167], v228 offset:18432
	v_cmp_neq_f32_e32 vcc, 1.0, v232
	s_cbranch_vccz .Lat_nors_l2
	v_pk_mul_f32 v[0:1], v[0:1], v[232:233] op_sel_hi:[1,0]
	v_pk_mul_f32 v[2:3], v[2:3], v[232:233] op_sel_hi:[1,0]
	v_pk_mul_f32 v[4:5], v[4:5], v[232:233] op_sel_hi:[1,0]
	v_pk_mul_f32 v[6:7], v[6:7], v[232:233] op_sel_hi:[1,0]
	v_pk_mul_f32 v[8:9], v[8:9], v[232:233] op_sel_hi:[1,0]
	v_pk_mul_f32 v[10:11], v[10:11], v[232:233] op_sel_hi:[1,0]
	v_pk_mul_f32 v[12:13], v[12:13], v[232:233] op_sel_hi:[1,0]
	v_pk_mul_f32 v[14:15], v[14:15], v[232:233] op_sel_hi:[1,0]
	v_pk_mul_f32 v[16:17], v[16:17], v[232:233] op_sel_hi:[1,0]
	v_pk_mul_f32 v[18:19], v[18:19], v[232:233] op_sel_hi:[1,0]
	v_pk_mul_f32 v[20:21], v[20:21], v[232:233] op_sel_hi:[1,0]
	v_pk_mul_f32 v[22:23], v[22:23], v[232:233] op_sel_hi:[1,0]
	v_pk_mul_f32 v[24:25], v[24:25], v[232:233] op_sel_hi:[1,0]
	v_pk_mul_f32 v[26:27], v[26:27], v[232:233] op_sel_hi:[1,0]
	v_pk_mul_f32 v[28:29], v[28:29], v[232:233] op_sel_hi:[1,0]
	v_pk_mul_f32 v[30:31], v[30:31], v[232:233] op_sel_hi:[1,0]
.Lat_nors_l2:
	v_fmamk_f32 v34, v34, 0x3e38aa3b, v234
	v_fmamk_f32 v35, v35, 0x3e38aa3b, v234
	v_fmamk_f32 v36, v36, 0x3e38aa3b, v234
	ds_read_b64_tr_b16 v[168:169], v228 offset:19456
	s_waitcnt lgkmcnt(14)
	v_fmamk_f32 v37, v37, 0x3e38aa3b, v234
	v_fmamk_f32 v38, v38, 0x3e38aa3b, v234
	v_fmamk_f32 v39, v39, 0x3e38aa3b, v234
	ds_read_b64_tr_b16 v[170:171], v227 offset:20480
	s_waitcnt lgkmcnt(14)
	v_fmamk_f32 v40, v40, 0x3e38aa3b, v234
	v_fmamk_f32 v41, v41, 0x3e38aa3b, v234
	v_exp_f32_e32 v34, v34
	ds_read_b64_tr_b16 v[172:173], v227 offset:21504
	s_waitcnt lgkmcnt(14)
	v_exp_f32_e32 v35, v35
	v_exp_f32_e32 v36, v36
	v_exp_f32_e32 v37, v37
	ds_read_b64_tr_b16 v[174:175], v228 offset:20480
	s_waitcnt lgkmcnt(14)
	v_exp_f32_e32 v38, v38
	v_exp_f32_e32 v39, v39
	v_exp_f32_e32 v40, v40
	ds_read_b64_tr_b16 v[176:177], v228 offset:21504
	s_waitcnt lgkmcnt(14)
	v_exp_f32_e32 v41, v41
	v_add_f32_e32 v243, v34, v38
	v_add_f32_e32 v244, v35, v39
	ds_read_b64_tr_b16 v[178:179], v227 offset:22528
	s_waitcnt lgkmcnt(14)
	v_add_f32_e32 v245, v36, v40
	v_add_f32_e32 v246, v37, v41
	v_cvt_pk_bf16_f32 v34, v34, v35
	ds_read_b64_tr_b16 v[180:181], v227 offset:23552
	s_waitcnt lgkmcnt(14)
	v_cvt_pk_bf16_f32 v35, v36, v37
	v_cvt_pk_bf16_f32 v36, v38, v39
	v_cvt_pk_bf16_f32 v37, v40, v41
	ds_read_b64_tr_b16 v[182:183], v228 offset:22528
	s_waitcnt lgkmcnt(14)
	s_waitcnt lgkmcnt(13)
	v_mfma_f32_32x32x16_bf16 v[0:15], v[154:157], v[34:37], v[0:15]
	s_waitcnt lgkmcnt(11)
	v_mfma_f32_32x32x16_bf16 v[16:31], v[158:161], v[34:37], v[16:31]
	v_fmamk_f32 v42, v42, 0x3e38aa3b, v234
	v_fmamk_f32 v43, v43, 0x3e38aa3b, v234
	v_fmamk_f32 v44, v44, 0x3e38aa3b, v234
	ds_read_b64_tr_b16 v[184:185], v228 offset:23552
	v_fmamk_f32 v45, v45, 0x3e38aa3b, v234
	v_fmamk_f32 v46, v46, 0x3e38aa3b, v234
	v_fmamk_f32 v47, v47, 0x3e38aa3b, v234
	v_fmamk_f32 v48, v48, 0x3e38aa3b, v234
	v_fmamk_f32 v49, v49, 0x3e38aa3b, v234
	v_exp_f32_e32 v42, v42
	v_exp_f32_e32 v43, v43
	v_exp_f32_e32 v44, v44
	v_exp_f32_e32 v45, v45
	v_exp_f32_e32 v46, v46
	v_exp_f32_e32 v47, v47
	v_exp_f32_e32 v48, v48
	v_exp_f32_e32 v49, v49
	v_add_f32_e32 v243, v243, v42
	v_add_f32_e32 v244, v244, v43
	v_add_f32_e32 v245, v245, v44
	v_add_f32_e32 v246, v246, v45
	v_add_f32_e32 v243, v243, v46
	v_add_f32_e32 v244, v244, v47
	v_add_f32_e32 v245, v245, v48
	v_add_f32_e32 v246, v246, v49
	v_cvt_pk_bf16_f32 v42, v42, v43
	v_cvt_pk_bf16_f32 v43, v44, v45
	v_cvt_pk_bf16_f32 v44, v46, v47
	v_cvt_pk_bf16_f32 v45, v48, v49
	s_waitcnt lgkmcnt(10)
	v_mfma_f32_32x32x16_bf16 v[0:15], v[162:165], v[42:45], v[0:15]
	s_waitcnt lgkmcnt(8)
	v_mfma_f32_32x32x16_bf16 v[16:31], v[166:169], v[42:45], v[16:31]
	v_fmamk_f32 v50, v50, 0x3e38aa3b, v234
	v_fmamk_f32 v51, v51, 0x3e38aa3b, v234
	v_fmamk_f32 v52, v52, 0x3e38aa3b, v234
	v_fmamk_f32 v53, v53, 0x3e38aa3b, v234
	v_fmamk_f32 v54, v54, 0x3e38aa3b, v234
	v_fmamk_f32 v55, v55, 0x3e38aa3b, v234
	v_fmamk_f32 v56, v56, 0x3e38aa3b, v234
	v_fmamk_f32 v57, v57, 0x3e38aa3b, v234
	v_exp_f32_e32 v50, v50
	v_exp_f32_e32 v51, v51
	v_exp_f32_e32 v52, v52
	v_exp_f32_e32 v53, v53
	v_exp_f32_e32 v54, v54
	v_exp_f32_e32 v55, v55
	v_exp_f32_e32 v56, v56
	v_exp_f32_e32 v57, v57
	v_add_f32_e32 v243, v243, v50
	v_add_f32_e32 v244, v244, v51
	v_add_f32_e32 v245, v245, v52
	v_add_f32_e32 v246, v246, v53
	v_add_f32_e32 v243, v243, v54
	v_add_f32_e32 v244, v244, v55
	v_add_f32_e32 v245, v245, v56
	v_add_f32_e32 v246, v246, v57
	v_cvt_pk_bf16_f32 v50, v50, v51
	v_cvt_pk_bf16_f32 v51, v52, v53
	v_cvt_pk_bf16_f32 v52, v54, v55
	v_cvt_pk_bf16_f32 v53, v56, v57
	s_waitcnt lgkmcnt(6)
	v_mfma_f32_32x32x16_bf16 v[0:15], v[170:173], v[50:53], v[0:15]
	s_waitcnt lgkmcnt(4)
	v_mfma_f32_32x32x16_bf16 v[16:31], v[174:177], v[50:53], v[16:31]
	v_fmamk_f32 v58, v58, 0x3e38aa3b, v234
	v_fmamk_f32 v59, v59, 0x3e38aa3b, v234
	v_fmamk_f32 v60, v60, 0x3e38aa3b, v234
	v_fmamk_f32 v61, v61, 0x3e38aa3b, v234
	v_fmamk_f32 v62, v62, 0x3e38aa3b, v234
	v_fmamk_f32 v63, v63, 0x3e38aa3b, v234
	v_fmamk_f32 v64, v64, 0x3e38aa3b, v234
	v_fmamk_f32 v65, v65, 0x3e38aa3b, v234
	v_exp_f32_e32 v58, v58
	v_exp_f32_e32 v59, v59
	v_exp_f32_e32 v60, v60
	v_exp_f32_e32 v61, v61
	v_exp_f32_e32 v62, v62
	v_exp_f32_e32 v63, v63
	v_exp_f32_e32 v64, v64
	v_exp_f32_e32 v65, v65
	v_add_f32_e32 v243, v243, v58
	v_add_f32_e32 v244, v244, v59
	v_add_f32_e32 v245, v245, v60
	v_add_f32_e32 v246, v246, v61
	v_add_f32_e32 v243, v243, v62
	v_add_f32_e32 v244, v244, v63
	v_add_f32_e32 v245, v245, v64
	v_add_f32_e32 v246, v246, v65
	v_cvt_pk_bf16_f32 v58, v58, v59
	v_cvt_pk_bf16_f32 v59, v60, v61
	v_cvt_pk_bf16_f32 v60, v62, v63
	v_cvt_pk_bf16_f32 v61, v64, v65
	v_add_f32_e32 v243, v243, v244
	v_add_f32_e32 v245, v245, v246
	v_add_f32_e32 v243, v243, v245
	v_fma_f32 v231, v231, v232, v243
	s_waitcnt lgkmcnt(2)
	v_mfma_f32_32x32x16_bf16 v[0:15], v[178:181], v[58:61], v[0:15]
	s_waitcnt lgkmcnt(0)
	v_mfma_f32_32x32x16_bf16 v[16:31], v[182:185], v[58:61], v[16:31]
	s_waitcnt vmcnt(3)
	s_barrier
	s_add_u32 s8, s8, 1
	s_cmp_lt_u32 s8, s9
	s_cbranch_scc1 .Lat_loop_3
	s_branch .Lat_epilogue
.Lat_loop_3:
	s_add_u32 s18, s8, 4
	s_min_u32 s18, s18, s11
	s_mul_i32 s18, s18, 0xb2c00
	s_add_u32 s12, s4, s18
	s_addc_u32 s13, s5, 0
	s_add_u32 s19, s8, 2
	s_min_u32 s19, s19, s11
	s_mul_i32 s18, s19, 0xb2c00
	s_add_u32 s14, s4, s18
	s_addc_u32 s15, s5, 0
	s_lshl_b32 s19, s19, 3
	s_add_u32 s16, s6, s19
	s_addc_u32 s17, s7, 0
	s_add_i32 m0, s58, 0x6000
	s_nop 0
	global_load_lds_dwordx4 v221, s[12:13]
	s_add_i32 m0, s58, 0xa000
	s_nop 0
	global_load_lds_dwordx4 v222, s[14:15]
	global_load_dwordx2 v[216:217], v219, s[16:17]
	s_cmp_lt_u32 s8, s10
	s_cbranch_scc1 .Lat_full_3
	s_cmp_eq_u32 s8, s10
	s_cbranch_scc1 .Lat_last_3

.Lat_nors_f3:
	v_fmamk_f32 v70, v70, 0x3e38aa3b, v234
	v_fmamk_f32 v71, v71, 0x3e38aa3b, v234
	s_waitcnt lgkmcnt(7)
	v_mfma_f32_32x32x16_bf16 v[34:49], v[118:121], v[102:105], 0
	ds_read_b64_tr_b16 v[154:155], v227 offset:24576
	ds_read_b64_tr_b16 v[156:157], v227 offset:25600
	v_fmamk_f32 v72, v72, 0x3e38aa3b, v234
	v_fmamk_f32 v73, v73, 0x3e38aa3b, v234
	v_fmamk_f32 v74, v74, 0x3e38aa3b, v234
	v_fmamk_f32 v75, v75, 0x3e38aa3b, v234
	v_fmamk_f32 v76, v76, 0x3e38aa3b, v234
	v_fmamk_f32 v77, v77, 0x3e38aa3b, v234
	v_exp_f32_e32 v70, v70
	v_exp_f32_e32 v71, v71
	v_exp_f32_e32 v72, v72
	v_exp_f32_e32 v73, v73
	v_exp_f32_e32 v74, v74
	v_exp_f32_e32 v75, v75
	s_waitcnt lgkmcnt(8)
	v_mfma_f32_32x32x16_bf16 v[50:65], v[122:125], v[102:105], 0
	ds_read_b64_tr_b16 v[158:159], v228 offset:24576
	ds_read_b64_tr_b16 v[160:161], v228 offset:25600
	v_exp_f32_e32 v76, v76
	v_exp_f32_e32 v77, v77
	v_add_f32_e32 v243, v70, v74
	v_add_f32_e32 v244, v71, v75
	v_add_f32_e32 v245, v72, v76
	v_add_f32_e32 v246, v73, v77
	v_cvt_pk_bf16_f32 v70, v70, v71
	v_cvt_pk_bf16_f32 v71, v72, v73
	v_cvt_pk_bf16_f32 v72, v74, v75
	v_cvt_pk_bf16_f32 v73, v76, v77
	v_fmamk_f32 v78, v78, 0x3e38aa3b, v234
	v_fmamk_f32 v79, v79, 0x3e38aa3b, v234
	s_waitcnt lgkmcnt(9)
	v_mfma_f32_32x32x16_bf16 v[34:49], v[126:129], v[106:109], v[34:49]
	ds_read_b64_tr_b16 v[162:163], v227 offset:26624
	ds_read_b64_tr_b16 v[164:165], v227 offset:27648
	v_fmamk_f32 v80, v80, 0x3e38aa3b, v234
	v_fmamk_f32 v81, v81, 0x3e38aa3b, v234
	v_fmamk_f32 v82, v82, 0x3e38aa3b, v234
	v_fmamk_f32 v83, v83, 0x3e38aa3b, v234
	v_fmamk_f32 v84, v84, 0x3e38aa3b, v234
	v_fmamk_f32 v85, v85, 0x3e38aa3b, v234
	v_exp_f32_e32 v78, v78
	v_exp_f32_e32 v79, v79
	v_exp_f32_e32 v80, v80
	v_exp_f32_e32 v81, v81
	v_exp_f32_e32 v82, v82
	v_exp_f32_e32 v83, v83
	s_waitcnt lgkmcnt(10)
	v_mfma_f32_32x32x16_bf16 v[50:65], v[130:133], v[106:109], v[50:65]
	ds_read_b64_tr_b16 v[166:167], v228 offset:26624
	ds_read_b64_tr_b16 v[168:169], v228 offset:27648
	v_exp_f32_e32 v84, v84
	v_exp_f32_e32 v85, v85
	v_add_f32_e32 v243, v243, v78
	v_add_f32_e32 v244, v244, v79
	v_add_f32_e32 v245, v245, v80
	v_add_f32_e32 v246, v246, v81
	v_add_f32_e32 v243, v243, v82
	v_add_f32_e32 v244, v244, v83
	v_add_f32_e32 v245, v245, v84
	v_add_f32_e32 v246, v246, v85
	v_cvt_pk_bf16_f32 v78, v78, v79
	v_cvt_pk_bf16_f32 v79, v80, v81
	s_waitcnt lgkmcnt(11)
	v_mfma_f32_32x32x16_bf16 v[34:49], v[134:137], v[110:113], v[34:49]
	ds_read_b64_tr_b16 v[170:171], v227 offset:28672
	ds_read_b64_tr_b16 v[172:173], v227 offset:29696
	v_cvt_pk_bf16_f32 v80, v82, v83
	v_cvt_pk_bf16_f32 v81, v84, v85
	v_fmamk_f32 v86, v86, 0x3e38aa3b, v234
	v_fmamk_f32 v87, v87, 0x3e38aa3b, v234
	v_fmamk_f32 v88, v88, 0x3e38aa3b, v234
	v_fmamk_f32 v89, v89, 0x3e38aa3b, v234
	v_fmamk_f32 v90, v90, 0x3e38aa3b, v234
	v_fmamk_f32 v91, v91, 0x3e38aa3b, v234
	v_fmamk_f32 v92, v92, 0x3e38aa3b, v234
	v_fmamk_f32 v93, v93, 0x3e38aa3b, v234
	v_exp_f32_e32 v86, v86
	v_exp_f32_e32 v87, v87
	s_waitcnt lgkmcnt(12)
	v_mfma_f32_32x32x16_bf16 v[50:65], v[138:141], v[110:113], v[50:65]
	ds_read_b64_tr_b16 v[174:175], v228 offset:28672
	ds_read_b64_tr_b16 v[176:177], v228 offset:29696
	v_exp_f32_e32 v88, v88
	v_exp_f32_e32 v89, v89
	v_exp_f32_e32 v90, v90
	v_exp_f32_e32 v91, v91
	v_exp_f32_e32 v92, v92
	v_exp_f32_e32 v93, v93
	v_add_f32_e32 v243, v243, v86
	v_add_f32_e32 v244, v244, v87
	v_add_f32_e32 v245, v245, v88
	v_add_f32_e32 v246, v246, v89
	v_add_f32_e32 v243, v243, v90
	v_add_f32_e32 v244, v244, v91
	s_waitcnt lgkmcnt(13)
	v_mfma_f32_32x32x16_bf16 v[34:49], v[142:145], v[114:117], v[34:49]
	ds_read_b64_tr_b16 v[178:179], v227 offset:30720
	ds_read_b64_tr_b16 v[180:181], v227 offset:31744
	v_add_f32_e32 v245, v245, v92
	v_add_f32_e32 v246, v246, v93
	v_cvt_pk_bf16_f32 v86, v86, v87
	v_cvt_pk_bf16_f32 v87, v88, v89
	v_cvt_pk_bf16_f32 v88, v90, v91
	v_cvt_pk_bf16_f32 v89, v92, v93
	v_fmamk_f32 v94, v94, 0x3e38aa3b, v234
	v_fmamk_f32 v95, v95, 0x3e38aa3b, v234
	v_fmamk_f32 v96, v96, 0x3e38aa3b, v234
	v_fmamk_f32 v97, v97, 0x3e38aa3b, v234
	v_fmamk_f32 v98, v98, 0x3e38aa3b, v234
	v_fmamk_f32 v99, v99, 0x3e38aa3b, v234
	s_waitcnt lgkmcnt(14)
	v_mfma_f32_32x32x16_bf16 v[50:65], v[146:149], v[114:117], v[50:65]
	ds_read_b64_tr_b16 v[182:183], v228 offset:30720
	ds_read_b64_tr_b16 v[184:185], v228 offset:31744
	s_waitcnt lgkmcnt(14)
	v_fmamk_f32 v100, v100, 0x3e38aa3b, v234
	v_fmamk_f32 v101, v101, 0x3e38aa3b, v234
	v_exp_f32_e32 v94, v94
	v_exp_f32_e32 v95, v95
	v_exp_f32_e32 v96, v96
	v_exp_f32_e32 v97, v97
	v_exp_f32_e32 v98, v98
	v_exp_f32_e32 v99, v99
	v_exp_f32_e32 v100, v100
	v_exp_f32_e32 v101, v101
	v_add_f32_e32 v243, v243, v94
	v_add_f32_e32 v244, v244, v95
	v_add_f32_e32 v245, v245, v96
	v_add_f32_e32 v246, v246, v97
	s_waitcnt lgkmcnt(14)
	v_mfma_f32_32x32x16_bf16 v[0:15], v[154:157], v[70:73], v[0:15]
	ds_read_b128 v[118:121], v223 offset:8192
	v_add_f32_e32 v243, v243, v98
	v_add_f32_e32 v244, v244, v99
	v_add_f32_e32 v245, v245, v100
	v_add_f32_e32 v246, v246, v101
	v_cvt_pk_bf16_f32 v94, v94, v95
	v_cvt_pk_bf16_f32 v95, v96, v97
	v_cvt_pk_bf16_f32 v96, v98, v99
	v_cvt_pk_bf16_f32 v97, v100, v101
	v_add_f32_e32 v243, v243, v244
	v_add_f32_e32 v245, v245, v246
	v_add_f32_e32 v243, v243, v245
	v_fma_f32 v231, v231, v232, v243
	s_waitcnt lgkmcnt(13)
	v_mfma_f32_32x32x16_bf16 v[16:31], v[158:161], v[70:73], v[16:31]
	ds_read_b128 v[122:125], v223 offset:12288
	s_waitcnt vmcnt(3)
	v_lshrrev_b32_e32 v249, v229, v214
	v_lshrrev_b32_e32 v250, v229, v215
	v_bfe_i32 v235, v249, 0, 1
	v_bfe_i32 v236, v250, 0, 1
	v_bfe_i32 v237, v249, 1, 1
	v_bfe_i32 v238, v250, 1, 1
	v_bfe_i32 v239, v249, 2, 1
	v_bfe_i32 v240, v250, 2, 1
	v_bfe_i32 v241, v249, 3, 1
	v_bfe_i32 v242, v250, 3, 1
	v_bitop3_b32 v34, v34, s33, v235 bitop3:0xe4
	s_waitcnt lgkmcnt(12)
	v_mfma_f32_32x32x16_bf16 v[0:15], v[162:165], v[78:81], v[0:15]
	ds_read_b128 v[126:129], v224 offset:8192
	v_bitop3_b32 v50, v50, s33, v236 bitop3:0xe4
	v_bitop3_b32 v35, v35, s33, v237 bitop3:0xe4
	v_bitop3_b32 v51, v51, s33, v238 bitop3:0xe4
	v_bitop3_b32 v36, v36, s33, v239 bitop3:0xe4
	v_bitop3_b32 v52, v52, s33, v240 bitop3:0xe4
	v_bitop3_b32 v37, v37, s33, v241 bitop3:0xe4
	v_bitop3_b32 v53, v53, s33, v242 bitop3:0xe4
	v_max3_f32 v247, v34, s33, v50
	v_max3_f32 v248, v35, s33, v51
	v_max3_f32 v247, v247, v36, v52
	v_max3_f32 v248, v248, v37, v53
	v_bfe_i32 v235, v249, 8, 1
	s_waitcnt lgkmcnt(11)
	v_mfma_f32_32x32x16_bf16 v[16:31], v[166:169], v[78:81], v[16:31]
	ds_read_b128 v[130:133], v224 offset:12288
	v_bfe_i32 v236, v250, 8, 1
	v_bfe_i32 v237, v249, 9, 1
	v_bfe_i32 v238, v250, 9, 1
	v_bfe_i32 v239, v249, 10, 1
	v_bfe_i32 v240, v250, 10, 1
	v_bfe_i32 v241, v249, 11, 1
	v_bfe_i32 v242, v250, 11, 1
	v_bitop3_b32 v38, v38, s33, v235 bitop3:0xe4
	v_bitop3_b32 v54, v54, s33, v236 bitop3:0xe4
	v_bitop3_b32 v39, v39, s33, v237 bitop3:0xe4
	v_bitop3_b32 v55, v55, s33, v238 bitop3:0xe4
	v_bitop3_b32 v40, v40, s33, v239 bitop3:0xe4
	s_waitcnt lgkmcnt(10)
	v_mfma_f32_32x32x16_bf16 v[0:15], v[170:173], v[86:89], v[0:15]
	ds_read_b128 v[134:137], v225 offset:8192
	v_bitop3_b32 v56, v56, s33, v240 bitop3:0xe4
	v_bitop3_b32 v41, v41, s33, v241 bitop3:0xe4
	v_bitop3_b32 v57, v57, s33, v242 bitop3:0xe4
	v_max3_f32 v247, v247, v38, v54
	v_max3_f32 v248, v248, v39, v55
	v_max3_f32 v247, v247, v40, v56
	v_max3_f32 v248, v248, v41, v57
	v_bfe_i32 v235, v249, 16, 1
	v_bfe_i32 v236, v250, 16, 1
	v_bfe_i32 v237, v249, 17, 1
	v_bfe_i32 v238, v250, 17, 1
	v_bfe_i32 v239, v249, 18, 1
	s_waitcnt lgkmcnt(9)
	v_mfma_f32_32x32x16_bf16 v[16:31], v[174:177], v[86:89], v[16:31]
	ds_read_b128 v[138:141], v225 offset:12288
	v_bfe_i32 v240, v250, 18, 1
	v_bfe_i32 v241, v249, 19, 1
	v_bfe_i32 v242, v250, 19, 1
	v_bitop3_b32 v42, v42, s33, v235 bitop3:0xe4
	v_bitop3_b32 v58, v58, s33, v236 bitop3:0xe4
	v_bitop3_b32 v43, v43, s33, v237 bitop3:0xe4
	v_bitop3_b32 v59, v59, s33, v238 bitop3:0xe4
	v_bitop3_b32 v44, v44, s33, v239 bitop3:0xe4
	v_bitop3_b32 v60, v60, s33, v240 bitop3:0xe4
	v_bitop3_b32 v45, v45, s33, v241 bitop3:0xe4
	v_bitop3_b32 v61, v61, s33, v242 bitop3:0xe4
	v_max3_f32 v247, v247, v42, v58
	s_waitcnt lgkmcnt(8)
	v_mfma_f32_32x32x16_bf16 v[0:15], v[178:181], v[94:97], v[0:15]
	ds_read_b128 v[142:145], v226 offset:8192
	v_max3_f32 v248, v248, v43, v59
	v_max3_f32 v247, v247, v44, v60
	v_max3_f32 v248, v248, v45, v61
	v_bfe_i32 v235, v249, 24, 1
	v_bfe_i32 v236, v250, 24, 1
	v_bfe_i32 v237, v249, 25, 1
	v_bfe_i32 v238, v250, 25, 1
	v_bfe_i32 v239, v249, 26, 1
	v_bfe_i32 v240, v250, 26, 1
	v_bfe_i32 v241, v249, 27, 1
	v_bfe_i32 v242, v250, 27, 1
	v_bitop3_b32 v46, v46, s33, v235 bitop3:0xe4
	s_waitcnt lgkmcnt(7)
	v_mfma_f32_32x32x16_bf16 v[16:31], v[182:185], v[94:97], v[16:31]
	ds_read_b128 v[146:149], v226 offset:12288
	v_bitop3_b32 v62, v62, s33, v236 bitop3:0xe4
	v_bitop3_b32 v47, v47, s33, v237 bitop3:0xe4
	v_bitop3_b32 v63, v63, s33, v238 bitop3:0xe4
	v_bitop3_b32 v48, v48, s33, v239 bitop3:0xe4
	v_bitop3_b32 v64, v64, s33, v240 bitop3:0xe4
	v_bitop3_b32 v49, v49, s33, v241 bitop3:0xe4
	v_bitop3_b32 v65, v65, s33, v242 bitop3:0xe4
	v_max3_f32 v247, v247, v46, v62
	v_max3_f32 v248, v248, v47, v63
	v_max3_f32 v247, v247, v48, v64
	v_max3_f32 v248, v248, v49, v65
	v_max_f32_e32 v247, v247, v248
	v_mov_b32_e32 v248, v247
	s_nop 1
	v_permlane32_swap_b32_e32 v247, v248
	v_max3_f32 v247, v230, v247, v248
	v_cmp_neq_f32_e32 vcc, s33, v247
	s_nop 1
	v_cndmask_b32_e32 v248, 0, v247, vcc
	v_sub_f32_e32 v33, v230, v248
	v_mul_f32_e32 v33, 0x3e38aa3b, v33
	v_exp_f32_e32 v232, v33
	v_mul_f32_e32 v234, 0xbe38aa3b, v248
	v_mov_b32_e32 v230, v247
	s_waitcnt vmcnt(3)
	s_barrier
	s_add_u32 s8, s8, 1
	s_cmp_lt_u32 s8, s9
	s_cbranch_scc1 .Lat_loop_0
	s_branch .Lat_epilogue
.Lat_last_3:
	ds_read_b64_tr_b16 v[154:155], v227 offset:24576
	ds_read_b64_tr_b16 v[156:157], v227 offset:25600
	ds_read_b64_tr_b16 v[158:159], v228 offset:24576
	ds_read_b64_tr_b16 v[160:161], v228 offset:25600
	ds_read_b64_tr_b16 v[162:163], v227 offset:26624
	ds_read_b64_tr_b16 v[164:165], v227 offset:27648
	ds_read_b64_tr_b16 v[166:167], v228 offset:26624
	v_cmp_neq_f32_e32 vcc, 1.0, v232
	s_cbranch_vccz .Lat_nors_l3
	v_pk_mul_f32 v[0:1], v[0:1], v[232:233] op_sel_hi:[1,0]
	v_pk_mul_f32 v[2:3], v[2:3], v[232:233] op_sel_hi:[1,0]
	v_pk_mul_f32 v[4:5], v[4:5], v[232:233] op_sel_hi:[1,0]
	v_pk_mul_f32 v[6:7], v[6:7], v[232:233] op_sel_hi:[1,0]
	v_pk_mul_f32 v[8:9], v[8:9], v[232:233] op_sel_hi:[1,0]
	v_pk_mul_f32 v[10:11], v[10:11], v[232:233] op_sel_hi:[1,0]
	v_pk_mul_f32 v[12:13], v[12:13], v[232:233] op_sel_hi:[1,0]
	v_pk_mul_f32 v[14:15], v[14:15], v[232:233] op_sel_hi:[1,0]
	v_pk_mul_f32 v[16:17], v[16:17], v[232:233] op_sel_hi:[1,0]
	v_pk_mul_f32 v[18:19], v[18:19], v[232:233] op_sel_hi:[1,0]
	v_pk_mul_f32 v[20:21], v[20:21], v[232:233] op_sel_hi:[1,0]
	v_pk_mul_f32 v[22:23], v[22:23], v[232:233] op_sel_hi:[1,0]
	v_pk_mul_f32 v[24:25], v[24:25], v[232:233] op_sel_hi:[1,0]
	v_pk_mul_f32 v[26:27], v[26:27], v[232:233] op_sel_hi:[1,0]
	v_pk_mul_f32 v[28:29], v[28:29], v[232:233] op_sel_hi:[1,0]
	v_pk_mul_f32 v[30:31], v[30:31], v[232:233] op_sel_hi:[1,0]
.Lat_nors_l3:
	v_fmamk_f32 v70, v70, 0x3e38aa3b, v234
	v_fmamk_f32 v71, v71, 0x3e38aa3b, v234
	v_fmamk_f32 v72, v72, 0x3e38aa3b, v234
	ds_read_b64_tr_b16 v[168:169], v228 offset:27648
	s_waitcnt lgkmcnt(14)
	v_fmamk_f32 v73, v73, 0x3e38aa3b, v234
	v_fmamk_f32 v74, v74, 0x3e38aa3b, v234
	v_fmamk_f32 v75, v75, 0x3e38aa3b, v234
	ds_read_b64_tr_b16 v[170:171], v227 offset:28672
	s_waitcnt lgkmcnt(14)
	v_fmamk_f32 v76, v76, 0x3e38aa3b, v234
	v_fmamk_f32 v77, v77, 0x3e38aa3b, v234
	v_exp_f32_e32 v70, v70
	ds_read_b64_tr_b16 v[172:173], v227 offset:29696
	s_waitcnt lgkmcnt(14)
	v_exp_f32_e32 v71, v71
	v_exp_f32_e32 v72, v72
	v_exp_f32_e32 v73, v73
	ds_read_b64_tr_b16 v[174:175], v228 offset:28672
	s_waitcnt lgkmcnt(14)
	v_exp_f32_e32 v74, v74
	v_exp_f32_e32 v75, v75
	v_exp_f32_e32 v76, v76
	ds_read_b64_tr_b16 v[176:177], v228 offset:29696
	s_waitcnt lgkmcnt(14)
	v_exp_f32_e32 v77, v77
	v_add_f32_e32 v243, v70, v74
	v_add_f32_e32 v244, v71, v75
	ds_read_b64_tr_b16 v[178:179], v227 offset:30720
	s_waitcnt lgkmcnt(14)
	v_add_f32_e32 v245, v72, v76
	v_add_f32_e32 v246, v73, v77
	v_cvt_pk_bf16_f32 v70, v70, v71
	ds_read_b64_tr_b16 v[180:181], v227 offset:31744
	s_waitcnt lgkmcnt(14)
	v_cvt_pk_bf16_f32 v71, v72, v73
	v_cvt_pk_bf16_f32 v72, v74, v75
	v_cvt_pk_bf16_f32 v73, v76, v77
	ds_read_b64_tr_b16 v[182:183], v228 offset:30720
	s_waitcnt lgkmcnt(14)
	s_waitcnt lgkmcnt(13)
	v_mfma_f32_32x32x16_bf16 v[0:15], v[154:157], v[70:73], v[0:15]
	s_waitcnt lgkmcnt(11)
	v_mfma_f32_32x32x16_bf16 v[16:31], v[158:161], v[70:73], v[16:31]
	v_fmamk_f32 v78, v78, 0x3e38aa3b, v234
	v_fmamk_f32 v79, v79, 0x3e38aa3b, v234
	v_fmamk_f32 v80, v80, 0x3e38aa3b, v234
	ds_read_b64_tr_b16 v[184:185], v228 offset:31744
	v_fmamk_f32 v81, v81, 0x3e38aa3b, v234
	v_fmamk_f32 v82, v82, 0x3e38aa3b, v234
	v_fmamk_f32 v83, v83, 0x3e38aa3b, v234
	v_fmamk_f32 v84, v84, 0x3e38aa3b, v234
	v_fmamk_f32 v85, v85, 0x3e38aa3b, v234
	v_exp_f32_e32 v78, v78
	v_exp_f32_e32 v79, v79
	v_exp_f32_e32 v80, v80
	v_exp_f32_e32 v81, v81
	v_exp_f32_e32 v82, v82
	v_exp_f32_e32 v83, v83
	v_exp_f32_e32 v84, v84
	v_exp_f32_e32 v85, v85
	v_add_f32_e32 v243, v243, v78
	v_add_f32_e32 v244, v244, v79
	v_add_f32_e32 v245, v245, v80
	v_add_f32_e32 v246, v246, v81
	v_add_f32_e32 v243, v243, v82
	v_add_f32_e32 v244, v244, v83
	v_add_f32_e32 v245, v245, v84
	v_add_f32_e32 v246, v246, v85
	v_cvt_pk_bf16_f32 v78, v78, v79
	v_cvt_pk_bf16_f32 v79, v80, v81
	v_cvt_pk_bf16_f32 v80, v82, v83
	v_cvt_pk_bf16_f32 v81, v84, v85
	s_waitcnt lgkmcnt(10)
	v_mfma_f32_32x32x16_bf16 v[0:15], v[162:165], v[78:81], v[0:15]
	s_waitcnt lgkmcnt(8)
	v_mfma_f32_32x32x16_bf16 v[16:31], v[166:169], v[78:81], v[16:31]
	v_fmamk_f32 v86, v86, 0x3e38aa3b, v234
	v_fmamk_f32 v87, v87, 0x3e38aa3b, v234
	v_fmamk_f32 v88, v88, 0x3e38aa3b, v234
	v_fmamk_f32 v89, v89, 0x3e38aa3b, v234
	v_fmamk_f32 v90, v90, 0x3e38aa3b, v234
	v_fmamk_f32 v91, v91, 0x3e38aa3b, v234
	v_fmamk_f32 v92, v92, 0x3e38aa3b, v234
	v_fmamk_f32 v93, v93, 0x3e38aa3b, v234
	v_exp_f32_e32 v86, v86
	v_exp_f32_e32 v87, v87
	v_exp_f32_e32 v88, v88
	v_exp_f32_e32 v89, v89
	v_exp_f32_e32 v90, v90
	v_exp_f32_e32 v91, v91
	v_exp_f32_e32 v92, v92
	v_exp_f32_e32 v93, v93
	v_add_f32_e32 v243, v243, v86
	v_add_f32_e32 v244, v244, v87
	v_add_f32_e32 v245, v245, v88
	v_add_f32_e32 v246, v246, v89
	v_add_f32_e32 v243, v243, v90
	v_add_f32_e32 v244, v244, v91
	v_add_f32_e32 v245, v245, v92
	v_add_f32_e32 v246, v246, v93
	v_cvt_pk_bf16_f32 v86, v86, v87
	v_cvt_pk_bf16_f32 v87, v88, v89
	v_cvt_pk_bf16_f32 v88, v90, v91
	v_cvt_pk_bf16_f32 v89, v92, v93
	s_waitcnt lgkmcnt(6)
	v_mfma_f32_32x32x16_bf16 v[0:15], v[170:173], v[86:89], v[0:15]
	s_waitcnt lgkmcnt(4)
	v_mfma_f32_32x32x16_bf16 v[16:31], v[174:177], v[86:89], v[16:31]
	v_fmamk_f32 v94, v94, 0x3e38aa3b, v234
	v_fmamk_f32 v95, v95, 0x3e38aa3b, v234
	v_fmamk_f32 v96, v96, 0x3e38aa3b, v234
	v_fmamk_f32 v97, v97, 0x3e38aa3b, v234
	v_fmamk_f32 v98, v98, 0x3e38aa3b, v234
	v_fmamk_f32 v99, v99, 0x3e38aa3b, v234
	v_fmamk_f32 v100, v100, 0x3e38aa3b, v234
	v_fmamk_f32 v101, v101, 0x3e38aa3b, v234
	v_exp_f32_e32 v94, v94
	v_exp_f32_e32 v95, v95
	v_exp_f32_e32 v96, v96
	v_exp_f32_e32 v97, v97
	v_exp_f32_e32 v98, v98
	v_exp_f32_e32 v99, v99
	v_exp_f32_e32 v100, v100
	v_exp_f32_e32 v101, v101
	v_add_f32_e32 v243, v243, v94
	v_add_f32_e32 v244, v244, v95
	v_add_f32_e32 v245, v245, v96
	v_add_f32_e32 v246, v246, v97
	v_add_f32_e32 v243, v243, v98
	v_add_f32_e32 v244, v244, v99
	v_add_f32_e32 v245, v245, v100
	v_add_f32_e32 v246, v246, v101
	v_cvt_pk_bf16_f32 v94, v94, v95
	v_cvt_pk_bf16_f32 v95, v96, v97
	v_cvt_pk_bf16_f32 v96, v98, v99
	v_cvt_pk_bf16_f32 v97, v100, v101
	v_add_f32_e32 v243, v243, v244
	v_add_f32_e32 v245, v245, v246
	v_add_f32_e32 v243, v243, v245
	v_fma_f32 v231, v231, v232, v243
	s_waitcnt lgkmcnt(2)
	v_mfma_f32_32x32x16_bf16 v[0:15], v[178:181], v[94:97], v[0:15]
	s_waitcnt lgkmcnt(0)
	v_mfma_f32_32x32x16_bf16 v[16:31], v[182:185], v[94:97], v[16:31]
	s_waitcnt vmcnt(3)
	s_barrier
	s_add_u32 s8, s8, 1
	s_cmp_lt_u32 s8, s9
	s_cbranch_scc1 .Lat_loop_0
	s_branch .Lat_epilogue
.Lat_epilogue:
	v_mov_b32_e32 v248, v231
	v_mov_b32_e32 v247, v231
	s_nop 1
	v_permlane32_swap_b32_e32 v247, v248
	v_add_f32_e32 v247, v247, v248
	v_div_scale_f32 v235, s[18:19], v247, v247, 1.0
	v_rcp_f32_e32 v236, v235
	v_div_scale_f32 v237, vcc, 1.0, v247, 1.0
	v_fma_f32 v238, -v235, v236, 1.0
	v_fmac_f32_e32 v236, v238, v236
	v_mul_f32_e32 v238, v237, v236
	v_fma_f32 v239, -v235, v238, v237
	v_fmac_f32_e32 v238, v239, v236
	v_fma_f32 v235, -v235, v238, v237
	v_div_fmas_f32 v235, v235, v236, v238
	v_div_fixup_f32 v33, v235, v247, 1.0
	v_mul_f32_e32 v235, v0, v33
	v_mul_f32_e32 v236, v1, v33
	v_mul_f32_e32 v237, v2, v33
	v_mul_f32_e32 v238, v3, v33
	v_cvt_pk_bf16_f32 v240, v235, v236
	v_cvt_pk_bf16_f32 v241, v237, v238
	global_store_dwordx2 v197, v[240:241], s[4:5] offset:0
	s_nop 0
	v_mul_f32_e32 v235, v4, v33
	v_mul_f32_e32 v236, v5, v33
	v_mul_f32_e32 v237, v6, v33
	v_mul_f32_e32 v238, v7, v33
	v_cvt_pk_bf16_f32 v240, v235, v236
	v_cvt_pk_bf16_f32 v241, v237, v238
	global_store_dwordx2 v197, v[240:241], s[4:5] offset:16
	s_nop 0
	v_mul_f32_e32 v235, v8, v33
	v_mul_f32_e32 v236, v9, v33
	v_mul_f32_e32 v237, v10, v33
	v_mul_f32_e32 v238, v11, v33
	v_cvt_pk_bf16_f32 v240, v235, v236
	v_cvt_pk_bf16_f32 v241, v237, v238
	global_store_dwordx2 v197, v[240:241], s[4:5] offset:32
	s_nop 0
	v_mul_f32_e32 v235, v12, v33
	v_mul_f32_e32 v236, v13, v33
	v_mul_f32_e32 v237, v14, v33
	v_mul_f32_e32 v238, v15, v33
	v_cvt_pk_bf16_f32 v240, v235, v236
	v_cvt_pk_bf16_f32 v241, v237, v238
	global_store_dwordx2 v197, v[240:241], s[4:5] offset:48
	s_nop 0
	v_mul_f32_e32 v235, v16, v33
	v_mul_f32_e32 v236, v17, v33
	v_mul_f32_e32 v237, v18, v33
	v_mul_f32_e32 v238, v19, v33
	v_cvt_pk_bf16_f32 v240, v235, v236
	v_cvt_pk_bf16_f32 v241, v237, v238
	global_store_dwordx2 v197, v[240:241], s[4:5] offset:64
	s_nop 0
	v_mul_f32_e32 v235, v20, v33
	v_mul_f32_e32 v236, v21, v33
	v_mul_f32_e32 v237, v22, v33
	v_mul_f32_e32 v238, v23, v33
	v_cvt_pk_bf16_f32 v240, v235, v236
	v_cvt_pk_bf16_f32 v241, v237, v238
	global_store_dwordx2 v197, v[240:241], s[4:5] offset:80
	s_nop 0
	v_mul_f32_e32 v235, v24, v33
	v_mul_f32_e32 v236, v25, v33
	v_mul_f32_e32 v237, v26, v33
	v_mul_f32_e32 v238, v27, v33
	v_cvt_pk_bf16_f32 v240, v235, v236
	v_cvt_pk_bf16_f32 v241, v237, v238
	global_store_dwordx2 v197, v[240:241], s[4:5] offset:96
	s_nop 0
	v_mul_f32_e32 v235, v28, v33
	v_mul_f32_e32 v236, v29, v33
	v_mul_f32_e32 v237, v30, v33
	v_mul_f32_e32 v238, v31, v33
	v_cvt_pk_bf16_f32 v240, v235, v236
	v_cvt_pk_bf16_f32 v241, v237, v238
	global_store_dwordx2 v197, v[240:241], s[4:5] offset:112
	s_nop 0
	s_add_u32 s1, s1, 1
	s_cmp_lt_u32 s1, 2
	s_cbranch_scc1 .Lat_unit
	s_add_u32 s0, s0, s84
	s_branch .Lat_item
.Lat_exit:
	s_waitcnt vmcnt(0)
	s_mov_b32 s58, s84
	s_movk_i32 s83, 0x2cb0
	s_branch .LBB0_829
